# v072 + GEMM loops: handoff between the two wave halves shortened (duplicate lgkmcnt(0) wait after the opening barrier removed; priority lowered after, not before, the closing barrier)
# speedup vs baseline: 1.0156x; 1.0156x over previous
; #define PG8_STAGE(bufoff, gbase, voff) do { _Pragma("unroll") for (int _i = 0; _i < 2; ++_i) \
;         __builtin_amdgcn_global_load_lds((const gunsigned*)((const gchar*)(gbase) + (voff)[_i]), (LAS unsigned*)(lds + (bufoff) + ldsw + _i * 8192), 16, 0, 0); } while (0)
; #define PG8_LDA(dst, b, h) do { _Pragma("unroll") for (int m = 0; m < 4; ++m) _Pragma("unroll") for (int k = 0; k < 2; ++k) dst[m][k] = *(const LAS bf16x8*)(lds + PG8_SA(b, h) + aoff + m * 2048 + k * 1024); } while (0)
; #define PG8_LDB(dst, b, h) do { _Pragma("unroll") for (int n = 0; n < 2; ++n) _Pragma("unroll") for (int k = 0; k < 2; ++k) dst[n][k] = *(const LAS bf16x8*)(lds + PG8_SB(b, h) + boff + n * 2048 + k * 1024); } while (0)
; #define PG8_MMA(ai, bj, At, Bt) do { __builtin_amdgcn_s_setprio(1); _Pragma("unroll") for (int m = 0; m < 4; ++m) _Pragma("unroll") for (int n = 0; n < 2; ++n) _Pragma("unroll") for (int k = 0; k < 2; ++k) \
;         acc[ai][bj][m][n] = __builtin_amdgcn_mfma_f32_16x16x32_bf16(Bt[n][k], At[m][k], acc[ai][bj][m][n], 0, 0, 0); __builtin_amdgcn_s_setprio(0); } while (0)
; #define PG8_WAIT_V(n) asm volatile("s_waitcnt vmcnt(" #n ")" ::: "memory")
; #define PG8_WAIT_L(n) asm volatile("s_waitcnt lgkmcnt(" #n ")" ::: "memory")
; #define PG8_BAR __builtin_amdgcn_s_barrier()
; #define PG8_SCHED __builtin_amdgcn_sched_barrier(0)
; template <class Epi, class Sched>
; __device__ __forceinline__ void gemm_phase(LAS unsigned char* lds, const int tid, const Gemm g, const Sched& S, const Epi& E) {
;     ...
;             const bool last = (t == nt - 2);
;             const gchar* a1 = cA + (size_t)(t + 1) * kstep;
;             const gchar* a2 = last ? nA : cA + (size_t)(t + 2) * kstep; const gchar* b2 = last ? nB : cB + (size_t)(t + 2) * kstep;
;             const gchar* a3 = a2 + kstep; const gchar* b3 = b2 + kstep;
;             PG8_LDB(B0, 0, 0); PG8_LDB(B1, 0, 1); PG8_SCHED; PG8_LDA(At, 0, 0); PG8_STAGE(PG8_SA(1, 1), a1 + hstep, voffA);
;             PG8_WAIT_V(8); PG8_WAIT_L(0); PG8_BAR; PG8_MMA(0, 0, At, B0); PG8_MMA(0, 1, At, B1); PG8_BAR; PG8_SCHED;
;             PG8_LDA(At, 0, 1); PG8_STAGE(PG8_SB(0, 0), b2, voffB); PG8_STAGE(PG8_SB(0, 1), b2 + hstep, voffB); PG8_STAGE(PG8_SA(0, 0), a2, voffA);
;             PG8_WAIT_V(8); PG8_WAIT_L(0); PG8_BAR; PG8_MMA(1, 0, At, B0); PG8_MMA(1, 1, At, B1); PG8_BAR; PG8_SCHED;
.LBB0_319:
	s_add_u32 vcc_lo, s10, 0x100
	s_addc_u32 vcc_hi, s11, 0
	s_add_i32 s39, 0, 0x10000
	s_cmp_eq_u32 s29, 40
	s_cselect_b32 s75, s21, vcc_hi
	s_cselect_b32 s74, s20, vcc_lo
	s_cselect_b32 s73, s1, s93
	s_cselect_b32 s72, s0, s31
	s_add_i32 s30, 0, 0x14000
	v_add_u32_e32 v142, s39, v174
	v_add_u32_e32 v168, s30, v174
	ds_read_b128 v[130:133], v142
	ds_read_b128 v[134:137], v142 offset:1024
	ds_read_b128 v[138:141], v142 offset:2048
	ds_read_b128 v[142:145], v142 offset:3072
	ds_read_b128 v[146:149], v168
	ds_read_b128 v[150:153], v168 offset:1024
	ds_read_b128 v[164:167], v168 offset:2048
	ds_read_b128 v[168:171], v168 offset:3072
	s_add_i32 m0, s46, 0xc000
	ds_read_b128 v[192:195], v190
	ds_read_b128 v[204:207], v190 offset:1024
	ds_read_b128 v[208:211], v190 offset:2048
	ds_read_b128 v[212:215], v190 offset:3072
	ds_read_b128 v[216:219], v190 offset:4096
	ds_read_b128 v[220:223], v190 offset:5120
	ds_read_b128 v[224:227], v190 offset:6144
	ds_read_b128 v[242:245], v190 offset:7168
	global_load_lds_dwordx4 v162, s[10:11]
	s_add_i32 m0, s46, 0xe000
	s_nop 0
	global_load_lds_dwordx4 v160, s[10:11]
	s_waitcnt vmcnt(8)
	s_waitcnt lgkmcnt(0)
	s_barrier
	s_setprio 1
	v_mfma_f32_16x16x32_bf16 v[126:129], v[130:133], v[192:195], v[126:129]
	v_mfma_f32_16x16x32_bf16 v[122:125], v[138:141], v[192:195], v[122:125]
	v_mfma_f32_16x16x32_bf16 v[110:113], v[130:133], v[208:211], v[110:113]
	v_mfma_f32_16x16x32_bf16 v[106:109], v[138:141], v[208:211], v[106:109]
	v_mfma_f32_16x16x32_bf16 v[94:97], v[130:133], v[216:219], v[94:97]
	v_mfma_f32_16x16x32_bf16 v[90:93], v[138:141], v[216:219], v[90:93]
	v_mfma_f32_16x16x32_bf16 v[78:81], v[130:133], v[224:227], v[78:81]
	v_mfma_f32_16x16x32_bf16 v[74:77], v[138:141], v[224:227], v[74:77]
	v_mfma_f32_16x16x32_bf16 v[126:129], v[134:137], v[204:207], v[126:129]
	v_mfma_f32_16x16x32_bf16 v[122:125], v[142:145], v[204:207], v[122:125]
	v_mfma_f32_16x16x32_bf16 v[110:113], v[134:137], v[212:215], v[110:113]
	v_mfma_f32_16x16x32_bf16 v[106:109], v[142:145], v[212:215], v[106:109]
	v_mfma_f32_16x16x32_bf16 v[94:97], v[134:137], v[220:223], v[94:97]
	v_mfma_f32_16x16x32_bf16 v[90:93], v[142:145], v[220:223], v[90:93]
	v_mfma_f32_16x16x32_bf16 v[78:81], v[134:137], v[242:245], v[78:81]
	v_mfma_f32_16x16x32_bf16 v[74:77], v[142:145], v[242:245], v[74:77]
	s_setprio 0
	s_setprio 1
	v_mfma_f32_16x16x32_bf16 v[118:121], v[146:149], v[192:195], v[118:121]
	v_mfma_f32_16x16x32_bf16 v[114:117], v[164:167], v[192:195], v[114:117]
	v_mfma_f32_16x16x32_bf16 v[102:105], v[146:149], v[208:211], v[102:105]
	v_mfma_f32_16x16x32_bf16 v[98:101], v[164:167], v[208:211], v[98:101]
	v_mfma_f32_16x16x32_bf16 v[86:89], v[146:149], v[216:219], v[86:89]
	v_mfma_f32_16x16x32_bf16 v[82:85], v[164:167], v[216:219], v[82:85]
	v_mfma_f32_16x16x32_bf16 v[70:73], v[146:149], v[224:227], v[70:73]
	v_mfma_f32_16x16x32_bf16 v[66:69], v[164:167], v[224:227], v[66:69]
	v_mfma_f32_16x16x32_bf16 v[118:121], v[150:153], v[204:207], v[118:121]
	v_mfma_f32_16x16x32_bf16 v[114:117], v[168:171], v[204:207], v[114:117]
	v_mfma_f32_16x16x32_bf16 v[102:105], v[150:153], v[212:215], v[102:105]
	v_mfma_f32_16x16x32_bf16 v[98:101], v[168:171], v[212:215], v[98:101]
	v_mfma_f32_16x16x32_bf16 v[86:89], v[150:153], v[220:223], v[86:89]
	v_mfma_f32_16x16x32_bf16 v[82:85], v[168:171], v[220:223], v[82:85]
	v_mfma_f32_16x16x32_bf16 v[70:73], v[150:153], v[242:245], v[70:73]
	v_mfma_f32_16x16x32_bf16 v[66:69], v[168:171], v[242:245], v[66:69]
	s_barrier
	s_setprio 0
	s_add_i32 s10, s39, s43
	s_mov_b32 m0, s10
	ds_read_b128 v[192:195], v190 offset:16384
	ds_read_b128 v[204:207], v190 offset:17408
	ds_read_b128 v[208:211], v190 offset:18432
	ds_read_b128 v[212:215], v190 offset:19456
	ds_read_b128 v[216:219], v190 offset:20480
	ds_read_b128 v[220:223], v190 offset:21504
	ds_read_b128 v[224:227], v190 offset:22528
	ds_read_b128 v[242:245], v190 offset:23552
	global_load_lds_dwordx4 v0, s[72:73]
	s_add_i32 m0, s10, 0x2000
	s_add_u32 s10, s72, 0xb0000
	s_addc_u32 s11, s73, 0
	s_add_i32 s30, s30, s43
	global_load_lds_dwordx4 v158, s[72:73]
	s_mov_b32 m0, s30
	s_nop 0
	global_load_lds_dwordx4 v0, s[10:11]
	s_add_i32 m0, s30, 0x2000
	s_nop 0
	global_load_lds_dwordx4 v158, s[10:11]
	s_mov_b32 m0, s46
	s_nop 0
	global_load_lds_dwordx4 v154, s[74:75]
	s_mov_b32 m0, s47
	s_nop 0
	global_load_lds_dwordx4 v156, s[74:75]
	s_waitcnt vmcnt(8)
	s_waitcnt lgkmcnt(0)
	s_barrier
	s_setprio 1
	v_mfma_f32_16x16x32_bf16 v[62:65], v[130:133], v[192:195], v[62:65]
	v_mfma_f32_16x16x32_bf16 v[58:61], v[138:141], v[192:195], v[58:61]
	v_mfma_f32_16x16x32_bf16 v[46:49], v[130:133], v[208:211], v[46:49]
	v_mfma_f32_16x16x32_bf16 v[42:45], v[138:141], v[208:211], v[42:45]
	v_mfma_f32_16x16x32_bf16 v[30:33], v[130:133], v[216:219], v[30:33]
	v_mfma_f32_16x16x32_bf16 v[26:29], v[138:141], v[216:219], v[26:29]
	v_mfma_f32_16x16x32_bf16 v[14:17], v[130:133], v[224:227], v[14:17]
	v_mfma_f32_16x16x32_bf16 v[10:13], v[138:141], v[224:227], v[10:13]
	v_mfma_f32_16x16x32_bf16 v[62:65], v[134:137], v[204:207], v[62:65]
	v_mfma_f32_16x16x32_bf16 v[58:61], v[142:145], v[204:207], v[58:61]
	v_mfma_f32_16x16x32_bf16 v[46:49], v[134:137], v[212:215], v[46:49]
	v_mfma_f32_16x16x32_bf16 v[42:45], v[142:145], v[212:215], v[42:45]
	v_mfma_f32_16x16x32_bf16 v[30:33], v[134:137], v[220:223], v[30:33]
	v_mfma_f32_16x16x32_bf16 v[26:29], v[142:145], v[220:223], v[26:29]
	v_mfma_f32_16x16x32_bf16 v[14:17], v[134:137], v[242:245], v[14:17]
	v_mfma_f32_16x16x32_bf16 v[10:13], v[142:145], v[242:245], v[10:13]
	s_setprio 0
	s_setprio 1
	v_mfma_f32_16x16x32_bf16 v[54:57], v[146:149], v[192:195], v[54:57]
	v_mfma_f32_16x16x32_bf16 v[50:53], v[164:167], v[192:195], v[50:53]
	v_mfma_f32_16x16x32_bf16 v[38:41], v[146:149], v[208:211], v[38:41]
	v_mfma_f32_16x16x32_bf16 v[34:37], v[164:167], v[208:211], v[34:37]
	v_mfma_f32_16x16x32_bf16 v[22:25], v[146:149], v[216:219], v[22:25]
	v_mfma_f32_16x16x32_bf16 v[18:21], v[164:167], v[216:219], v[18:21]
	v_mfma_f32_16x16x32_bf16 v[6:9], v[146:149], v[224:227], v[6:9]
	v_mfma_f32_16x16x32_bf16 v[2:5], v[164:167], v[224:227], v[2:5]
	v_mfma_f32_16x16x32_bf16 v[54:57], v[150:153], v[204:207], v[54:57]
	v_mfma_f32_16x16x32_bf16 v[50:53], v[168:171], v[204:207], v[50:53]
	v_mfma_f32_16x16x32_bf16 v[38:41], v[150:153], v[212:215], v[38:41]
	v_mfma_f32_16x16x32_bf16 v[34:37], v[168:171], v[212:215], v[34:37]
	v_mfma_f32_16x16x32_bf16 v[22:25], v[150:153], v[220:223], v[22:25]
	v_mfma_f32_16x16x32_bf16 v[18:21], v[168:171], v[220:223], v[18:21]
	v_mfma_f32_16x16x32_bf16 v[6:9], v[150:153], v[242:245], v[6:9]
	v_mfma_f32_16x16x32_bf16 v[2:5], v[168:171], v[242:245], v[2:5]
	s_barrier
; #define PG8_STAGE(bufoff, gbase, voff) do { _Pragma("unroll") for (int _i = 0; _i < 2; ++_i) \
;         __builtin_amdgcn_global_load_lds((const gunsigned*)((const gchar*)(gbase) + (voff)[_i]), (LAS unsigned*)(lds + (bufoff) + ldsw + _i * 8192), 16, 0, 0); } while (0)
; #define PG8_LDA(dst, b, h) do { _Pragma("unroll") for (int m = 0; m < 4; ++m) _Pragma("unroll") for (int k = 0; k < 2; ++k) dst[m][k] = *(const LAS bf16x8*)(lds + PG8_SA(b, h) + aoff + m * 2048 + k * 1024); } while (0)
; #define PG8_LDB(dst, b, h) do { _Pragma("unroll") for (int n = 0; n < 2; ++n) _Pragma("unroll") for (int k = 0; k < 2; ++k) dst[n][k] = *(const LAS bf16x8*)(lds + PG8_SB(b, h) + boff + n * 2048 + k * 1024); } while (0)
; #define PG8_MMA(ai, bj, At, Bt) do { __builtin_amdgcn_s_setprio(1); _Pragma("unroll") for (int m = 0; m < 4; ++m) _Pragma("unroll") for (int n = 0; n < 2; ++n) _Pragma("unroll") for (int k = 0; k < 2; ++k) \
;         acc[ai][bj][m][n] = __builtin_amdgcn_mfma_f32_16x16x32_bf16(Bt[n][k], At[m][k], acc[ai][bj][m][n], 0, 0, 0); __builtin_amdgcn_s_setprio(0); } while (0)
; #define PG8_WAIT_V(n) asm volatile("s_waitcnt vmcnt(" #n ")" ::: "memory")
; #define PG8_WAIT_L(n) asm volatile("s_waitcnt lgkmcnt(" #n ")" ::: "memory")
; #define PG8_BAR __builtin_amdgcn_s_barrier()
; #define PG8_SCHED __builtin_amdgcn_sched_barrier(0)
; template <class Epi, class Sched>
; __device__ __forceinline__ void gemm_phase(LAS unsigned char* lds, const int tid, const Gemm g, const Sched& S, const Epi& E) {
;     ...
;             PG8_LDB(B0, 1, 0); PG8_LDB(B1, 1, 1); PG8_SCHED; PG8_LDA(At, 1, 0); PG8_STAGE(PG8_SA(0, 1), a2 + hstep, voffA);
;             PG8_WAIT_V(8); PG8_WAIT_L(0); PG8_BAR; PG8_MMA(0, 0, At, B0); PG8_MMA(0, 1, At, B1); PG8_BAR; PG8_SCHED;
;             PG8_LDA(At, 1, 1); PG8_STAGE(PG8_SB(1, 0), b3, voffB); PG8_STAGE(PG8_SB(1, 1), b3 + hstep, voffB); PG8_STAGE(PG8_SA(1, 0), a3, voffA);
;             PG8_WAIT_V(8); PG8_WAIT_L(0); PG8_BAR; PG8_MMA(1, 0, At, B0); PG8_MMA(1, 1, At, B1); PG8_BAR; PG8_SCHED;
;         }
;         if (wr == 0) PG8_BAR;
	s_setprio 0
	s_add_i32 s30, 0, 0x18000
	s_add_i32 s39, 0, 0x1c000
	v_add_u32_e32 v142, s30, v174
	v_add_u32_e32 v168, s39, v174
	ds_read_b128 v[130:133], v142
	ds_read_b128 v[134:137], v142 offset:1024
	ds_read_b128 v[138:141], v142 offset:2048
	ds_read_b128 v[142:145], v142 offset:3072
	ds_read_b128 v[146:149], v168
	ds_read_b128 v[150:153], v168 offset:1024
	ds_read_b128 v[164:167], v168 offset:2048
	ds_read_b128 v[168:171], v168 offset:3072
	s_add_u32 s10, s74, 0xb0000
	s_addc_u32 s11, s75, 0
	s_mov_b32 m0, s48
	ds_read_b128 v[192:195], v190 offset:32768
	ds_read_b128 v[204:207], v190 offset:33792
	ds_read_b128 v[208:211], v190 offset:34816
	ds_read_b128 v[212:215], v190 offset:35840
	ds_read_b128 v[216:219], v190 offset:36864
	ds_read_b128 v[220:223], v190 offset:37888
	ds_read_b128 v[224:227], v190 offset:38912
	ds_read_b128 v[242:245], v190 offset:39936
	global_load_lds_dwordx4 v154, s[10:11]
	s_mov_b32 m0, s49
	s_nop 0
	global_load_lds_dwordx4 v156, s[10:11]
	s_waitcnt vmcnt(8)
	s_waitcnt lgkmcnt(0)
	s_barrier
	s_setprio 1
	v_mfma_f32_16x16x32_bf16 v[126:129], v[130:133], v[192:195], v[126:129]
	v_mfma_f32_16x16x32_bf16 v[122:125], v[138:141], v[192:195], v[122:125]
	v_mfma_f32_16x16x32_bf16 v[110:113], v[130:133], v[208:211], v[110:113]
	v_mfma_f32_16x16x32_bf16 v[106:109], v[138:141], v[208:211], v[106:109]
	v_mfma_f32_16x16x32_bf16 v[94:97], v[130:133], v[216:219], v[94:97]
	v_mfma_f32_16x16x32_bf16 v[90:93], v[138:141], v[216:219], v[90:93]
	v_mfma_f32_16x16x32_bf16 v[78:81], v[130:133], v[224:227], v[78:81]
	v_mfma_f32_16x16x32_bf16 v[74:77], v[138:141], v[224:227], v[74:77]
	v_mfma_f32_16x16x32_bf16 v[126:129], v[134:137], v[204:207], v[126:129]
	v_mfma_f32_16x16x32_bf16 v[122:125], v[142:145], v[204:207], v[122:125]
	v_mfma_f32_16x16x32_bf16 v[110:113], v[134:137], v[212:215], v[110:113]
	v_mfma_f32_16x16x32_bf16 v[106:109], v[142:145], v[212:215], v[106:109]
	v_mfma_f32_16x16x32_bf16 v[94:97], v[134:137], v[220:223], v[94:97]
	v_mfma_f32_16x16x32_bf16 v[90:93], v[142:145], v[220:223], v[90:93]
	v_mfma_f32_16x16x32_bf16 v[78:81], v[134:137], v[242:245], v[78:81]
	v_mfma_f32_16x16x32_bf16 v[74:77], v[142:145], v[242:245], v[74:77]
	s_setprio 0
	s_setprio 1
	v_mfma_f32_16x16x32_bf16 v[118:121], v[146:149], v[192:195], v[118:121]
	v_mfma_f32_16x16x32_bf16 v[114:117], v[164:167], v[192:195], v[114:117]
	v_mfma_f32_16x16x32_bf16 v[102:105], v[146:149], v[208:211], v[102:105]
	v_mfma_f32_16x16x32_bf16 v[98:101], v[164:167], v[208:211], v[98:101]
	v_mfma_f32_16x16x32_bf16 v[86:89], v[146:149], v[216:219], v[86:89]
	v_mfma_f32_16x16x32_bf16 v[82:85], v[164:167], v[216:219], v[82:85]
	v_mfma_f32_16x16x32_bf16 v[70:73], v[146:149], v[224:227], v[70:73]
	v_mfma_f32_16x16x32_bf16 v[66:69], v[164:167], v[224:227], v[66:69]
	v_mfma_f32_16x16x32_bf16 v[118:121], v[150:153], v[204:207], v[118:121]
	v_mfma_f32_16x16x32_bf16 v[114:117], v[168:171], v[204:207], v[114:117]
	v_mfma_f32_16x16x32_bf16 v[102:105], v[150:153], v[212:215], v[102:105]
	v_mfma_f32_16x16x32_bf16 v[98:101], v[168:171], v[212:215], v[98:101]
	v_mfma_f32_16x16x32_bf16 v[86:89], v[150:153], v[220:223], v[86:89]
	v_mfma_f32_16x16x32_bf16 v[82:85], v[168:171], v[220:223], v[82:85]
	v_mfma_f32_16x16x32_bf16 v[70:73], v[150:153], v[242:245], v[70:73]
	v_mfma_f32_16x16x32_bf16 v[66:69], v[168:171], v[242:245], v[66:69]
	s_barrier
	s_setprio 0
	s_add_i32 s10, s30, s43
	s_mov_b32 m0, s10
	ds_read_b128 v[192:195], v190 offset:49152
	ds_read_b128 v[204:207], v190 offset:50176
	ds_read_b128 v[208:211], v190 offset:51200
	ds_read_b128 v[212:215], v190 offset:52224
	ds_read_b128 v[216:219], v190 offset:53248
	ds_read_b128 v[220:223], v190 offset:54272
	ds_read_b128 v[224:227], v190 offset:55296
	ds_read_b128 v[242:245], v190 offset:56320
	global_load_lds_dwordx4 v201, s[72:73]
	s_add_i32 m0, s10, 0x2000
	s_add_u32 s10, s72, 0xb0080
	s_addc_u32 s11, s73, 0
	s_add_i32 s30, s39, s43
	global_load_lds_dwordx4 v247, s[72:73]
	s_mov_b32 m0, s30
	s_nop 0
	global_load_lds_dwordx4 v0, s[10:11]
	s_add_i32 m0, s30, 0x2000
	s_nop 0
	global_load_lds_dwordx4 v158, s[10:11]
	s_mov_b32 m0, s53
	s_nop 0
	global_load_lds_dwordx4 v249, s[74:75]
	s_mov_b32 m0, s54
	s_nop 0
	global_load_lds_dwordx4 v251, s[74:75]
	s_waitcnt vmcnt(8)
	s_waitcnt lgkmcnt(0)
	s_barrier
	s_setprio 1
	v_mfma_f32_16x16x32_bf16 v[62:65], v[130:133], v[192:195], v[62:65]
	v_mfma_f32_16x16x32_bf16 v[58:61], v[138:141], v[192:195], v[58:61]
	v_mfma_f32_16x16x32_bf16 v[46:49], v[130:133], v[208:211], v[46:49]
	v_mfma_f32_16x16x32_bf16 v[42:45], v[138:141], v[208:211], v[42:45]
	v_mfma_f32_16x16x32_bf16 v[30:33], v[130:133], v[216:219], v[30:33]
	v_mfma_f32_16x16x32_bf16 v[26:29], v[138:141], v[216:219], v[26:29]
	v_mfma_f32_16x16x32_bf16 v[14:17], v[130:133], v[224:227], v[14:17]
	v_mfma_f32_16x16x32_bf16 v[10:13], v[138:141], v[224:227], v[10:13]
	v_mfma_f32_16x16x32_bf16 v[62:65], v[134:137], v[204:207], v[62:65]
	v_mfma_f32_16x16x32_bf16 v[58:61], v[142:145], v[204:207], v[58:61]
	v_mfma_f32_16x16x32_bf16 v[46:49], v[134:137], v[212:215], v[46:49]
	v_mfma_f32_16x16x32_bf16 v[42:45], v[142:145], v[212:215], v[42:45]
	v_mfma_f32_16x16x32_bf16 v[30:33], v[134:137], v[220:223], v[30:33]
	v_mfma_f32_16x16x32_bf16 v[26:29], v[142:145], v[220:223], v[26:29]
	v_mfma_f32_16x16x32_bf16 v[14:17], v[134:137], v[242:245], v[14:17]
	v_mfma_f32_16x16x32_bf16 v[10:13], v[142:145], v[242:245], v[10:13]
	s_setprio 0
	s_setprio 1
	v_mfma_f32_16x16x32_bf16 v[54:57], v[146:149], v[192:195], v[54:57]
	v_mfma_f32_16x16x32_bf16 v[50:53], v[164:167], v[192:195], v[50:53]
	v_mfma_f32_16x16x32_bf16 v[38:41], v[146:149], v[208:211], v[38:41]
	v_mfma_f32_16x16x32_bf16 v[34:37], v[164:167], v[208:211], v[34:37]
	v_mfma_f32_16x16x32_bf16 v[22:25], v[146:149], v[216:219], v[22:25]
	v_mfma_f32_16x16x32_bf16 v[18:21], v[164:167], v[216:219], v[18:21]
	v_mfma_f32_16x16x32_bf16 v[6:9], v[146:149], v[224:227], v[6:9]
	v_mfma_f32_16x16x32_bf16 v[2:5], v[164:167], v[224:227], v[2:5]
	v_mfma_f32_16x16x32_bf16 v[54:57], v[150:153], v[204:207], v[54:57]
	v_mfma_f32_16x16x32_bf16 v[50:53], v[168:171], v[204:207], v[50:53]
	v_mfma_f32_16x16x32_bf16 v[38:41], v[150:153], v[212:215], v[38:41]
	v_mfma_f32_16x16x32_bf16 v[34:37], v[168:171], v[212:215], v[34:37]
	v_mfma_f32_16x16x32_bf16 v[22:25], v[150:153], v[220:223], v[22:25]
	v_mfma_f32_16x16x32_bf16 v[18:21], v[168:171], v[220:223], v[18:21]
	v_mfma_f32_16x16x32_bf16 v[6:9], v[150:153], v[242:245], v[6:9]
	v_mfma_f32_16x16x32_bf16 v[2:5], v[168:171], v[242:245], v[2:5]
	s_barrier
	s_setprio 0
	s_add_i32 s29, s29, 2
	s_add_u32 s31, s31, 0x100
	s_addc_u32 s93, s93, 0
	s_cmp_gt_u32 s29, 41
	s_mov_b64 s[10:11], vcc
	s_cbranch_scc0 .LBB0_319
	s_and_b64 vcc, exec, s[16:17]
	s_cbranch_vccz .LBB0_322
	s_barrier

; #define PG8_STAGE(bufoff, gbase, voff) do { _Pragma("unroll") for (int _i = 0; _i < 2; ++_i) \
;         __builtin_amdgcn_global_load_lds((const gunsigned*)((const gchar*)(gbase) + (voff)[_i]), (LAS unsigned*)(lds + (bufoff) + ldsw + _i * 8192), 16, 0, 0); } while (0)
; #define PG8_LDA(dst, b, h) do { _Pragma("unroll") for (int m = 0; m < 4; ++m) _Pragma("unroll") for (int k = 0; k < 2; ++k) dst[m][k] = *(const LAS bf16x8*)(lds + PG8_SA(b, h) + aoff + m * 2048 + k * 1024); } while (0)
; #define PG8_LDB(dst, b, h) do { _Pragma("unroll") for (int n = 0; n < 2; ++n) _Pragma("unroll") for (int k = 0; k < 2; ++k) dst[n][k] = *(const LAS bf16x8*)(lds + PG8_SB(b, h) + boff + n * 2048 + k * 1024); } while (0)
; #define PG8_MMA(ai, bj, At, Bt) do { __builtin_amdgcn_s_setprio(1); _Pragma("unroll") for (int m = 0; m < 4; ++m) _Pragma("unroll") for (int n = 0; n < 2; ++n) _Pragma("unroll") for (int k = 0; k < 2; ++k) \
;         acc[ai][bj][m][n] = __builtin_amdgcn_mfma_f32_16x16x32_bf16(Bt[n][k], At[m][k], acc[ai][bj][m][n], 0, 0, 0); __builtin_amdgcn_s_setprio(0); } while (0)
; #define PG8_WAIT_V(n) asm volatile("s_waitcnt vmcnt(" #n ")" ::: "memory")
; #define PG8_WAIT_L(n) asm volatile("s_waitcnt lgkmcnt(" #n ")" ::: "memory")
; #define PG8_BAR __builtin_amdgcn_s_barrier()
; #define PG8_SCHED __builtin_amdgcn_sched_barrier(0)
; template <class Epi, class Sched>
; __device__ __forceinline__ void gemm_phase(LAS unsigned char* lds, const int tid, const Gemm g, const Sched& S, const Epi& E) {
;     ...
;             const bool last = (t == nt - 2);
;             const gchar* a1 = cA + (size_t)(t + 1) * kstep;
;             const gchar* a2 = last ? nA : cA + (size_t)(t + 2) * kstep; const gchar* b2 = last ? nB : cB + (size_t)(t + 2) * kstep;
;             const gchar* a3 = a2 + kstep; const gchar* b3 = b2 + kstep;
;             PG8_LDB(B0, 0, 0); PG8_LDB(B1, 0, 1); PG8_SCHED; PG8_LDA(At, 0, 0); PG8_STAGE(PG8_SA(1, 1), a1 + hstep, voffA);
;             PG8_WAIT_V(8); PG8_WAIT_L(0); PG8_BAR; PG8_MMA(0, 0, At, B0); PG8_MMA(0, 1, At, B1); PG8_BAR; PG8_SCHED;
;             PG8_LDA(At, 0, 1); PG8_STAGE(PG8_SB(0, 0), b2, voffB); PG8_STAGE(PG8_SB(0, 1), b2 + hstep, voffB); PG8_STAGE(PG8_SA(0, 0), a2, voffA);
;             PG8_WAIT_V(8); PG8_WAIT_L(0); PG8_BAR; PG8_MMA(1, 0, At, B0); PG8_MMA(1, 1, At, B1); PG8_BAR; PG8_SCHED;
.LBB0_369:
	s_add_u32 s20, s16, 0xfffc0080
	s_addc_u32 s21, s17, -1
	s_add_i32 s29, 0, 0x10000
	s_cmp_eq_u32 s31, 12
	s_cselect_b32 s57, s11, s21
	s_cselect_b32 s56, s12, s20
	v_add_u32_e32 v140, s29, v145
	s_cselect_b32 s21, s9, s24
	s_cselect_b32 s20, s15, s23
	s_add_i32 s30, 0, 0x14000
	ds_read_b128 v[146:149], v140
	ds_read_b128 v[156:159], v140 offset:1024
	ds_read_b128 v[160:163], v140 offset:2048
	ds_read_b128 v[164:167], v140 offset:3072
	v_add_u32_e32 v140, s30, v145
	ds_read_b128 v[168:171], v140
	ds_read_b128 v[172:175], v140 offset:1024
	ds_read_b128 v[176:179], v140 offset:2048
	ds_read_b128 v[180:183], v140 offset:3072
	s_add_i32 m0, s73, 0xc000
	ds_read_b128 v[184:187], v155
	ds_read_b128 v[188:191], v155 offset:1024
	ds_read_b128 v[192:195], v155 offset:2048
	ds_read_b128 v[204:207], v155 offset:3072
	ds_read_b128 v[208:211], v155 offset:4096
	ds_read_b128 v[212:215], v155 offset:5120
	ds_read_b128 v[216:219], v155 offset:6144
	ds_read_b128 v[220:223], v155 offset:7168
	global_load_lds_dwordx4 v138, s[16:17]
	s_add_i32 m0, s73, 0xe000
	s_nop 0
	global_load_lds_dwordx4 v136, s[16:17]
	s_waitcnt vmcnt(8)
	s_waitcnt lgkmcnt(0)
	s_barrier
	s_setprio 1
	v_mfma_f32_16x16x32_bf16 v[126:129], v[146:149], v[184:187], v[126:129]
	v_mfma_f32_16x16x32_bf16 v[118:121], v[160:163], v[184:187], v[118:121]
	v_mfma_f32_16x16x32_bf16 v[110:113], v[146:149], v[192:195], v[110:113]
	v_mfma_f32_16x16x32_bf16 v[102:105], v[160:163], v[192:195], v[102:105]
	v_mfma_f32_16x16x32_bf16 v[94:97], v[146:149], v[208:211], v[94:97]
	v_mfma_f32_16x16x32_bf16 v[86:89], v[160:163], v[208:211], v[86:89]
	v_mfma_f32_16x16x32_bf16 v[78:81], v[146:149], v[216:219], v[78:81]
	v_mfma_f32_16x16x32_bf16 v[70:73], v[160:163], v[216:219], v[70:73]
	v_mfma_f32_16x16x32_bf16 v[126:129], v[156:159], v[188:191], v[126:129]
	v_mfma_f32_16x16x32_bf16 v[118:121], v[164:167], v[188:191], v[118:121]
	v_mfma_f32_16x16x32_bf16 v[110:113], v[156:159], v[204:207], v[110:113]
	v_mfma_f32_16x16x32_bf16 v[102:105], v[164:167], v[204:207], v[102:105]
	v_mfma_f32_16x16x32_bf16 v[94:97], v[156:159], v[212:215], v[94:97]
	v_mfma_f32_16x16x32_bf16 v[86:89], v[164:167], v[212:215], v[86:89]
	v_mfma_f32_16x16x32_bf16 v[78:81], v[156:159], v[220:223], v[78:81]
	v_mfma_f32_16x16x32_bf16 v[70:73], v[164:167], v[220:223], v[70:73]
	s_setprio 0
	s_setprio 1
	v_mfma_f32_16x16x32_bf16 v[122:125], v[168:171], v[184:187], v[122:125]
	v_mfma_f32_16x16x32_bf16 v[114:117], v[176:179], v[184:187], v[114:117]
	v_mfma_f32_16x16x32_bf16 v[106:109], v[168:171], v[192:195], v[106:109]
	v_mfma_f32_16x16x32_bf16 v[98:101], v[176:179], v[192:195], v[98:101]
	v_mfma_f32_16x16x32_bf16 v[90:93], v[168:171], v[208:211], v[90:93]
	v_mfma_f32_16x16x32_bf16 v[82:85], v[176:179], v[208:211], v[82:85]
	v_mfma_f32_16x16x32_bf16 v[74:77], v[168:171], v[216:219], v[74:77]
	v_mfma_f32_16x16x32_bf16 v[66:69], v[176:179], v[216:219], v[66:69]
	v_mfma_f32_16x16x32_bf16 v[122:125], v[172:175], v[188:191], v[122:125]
	v_mfma_f32_16x16x32_bf16 v[114:117], v[180:183], v[188:191], v[114:117]
	v_mfma_f32_16x16x32_bf16 v[106:109], v[172:175], v[204:207], v[106:109]
	v_mfma_f32_16x16x32_bf16 v[98:101], v[180:183], v[204:207], v[98:101]
	v_mfma_f32_16x16x32_bf16 v[90:93], v[172:175], v[212:215], v[90:93]
	v_mfma_f32_16x16x32_bf16 v[82:85], v[180:183], v[212:215], v[82:85]
	v_mfma_f32_16x16x32_bf16 v[74:77], v[172:175], v[220:223], v[74:77]
	v_mfma_f32_16x16x32_bf16 v[66:69], v[180:183], v[220:223], v[66:69]
	s_barrier
	s_setprio 0
	s_add_i32 s29, s29, s43
	s_mov_b32 m0, s29
	ds_read_b128 v[184:187], v155 offset:16384
	ds_read_b128 v[188:191], v155 offset:17408
	ds_read_b128 v[192:195], v155 offset:18432
	ds_read_b128 v[204:207], v155 offset:19456
	ds_read_b128 v[208:211], v155 offset:20480
	ds_read_b128 v[212:215], v155 offset:21504
	ds_read_b128 v[216:219], v155 offset:22528
	ds_read_b128 v[220:223], v155 offset:23552
	global_load_lds_dwordx4 v0, s[20:21]
	s_add_i32 m0, s29, 0x2000
	s_add_u32 s46, s20, 0x40000
	s_addc_u32 s47, s21, 0
	s_add_i32 s29, s30, s43
	global_load_lds_dwordx4 v130, s[20:21]
	s_mov_b32 m0, s29
	s_nop 0
	global_load_lds_dwordx4 v0, s[46:47]
	s_add_i32 m0, s29, 0x2000
	s_nop 0
	global_load_lds_dwordx4 v130, s[46:47]
	s_mov_b32 m0, s73
	s_nop 0
	global_load_lds_dwordx4 v134, s[56:57]
	s_mov_b32 m0, s74
	s_nop 0
	global_load_lds_dwordx4 v132, s[56:57]
	s_waitcnt vmcnt(8)
	s_waitcnt lgkmcnt(0)
	s_barrier
	s_setprio 1
	v_mfma_f32_16x16x32_bf16 v[62:65], v[146:149], v[184:187], v[62:65]
	v_mfma_f32_16x16x32_bf16 v[54:57], v[160:163], v[184:187], v[54:57]
	v_mfma_f32_16x16x32_bf16 v[46:49], v[146:149], v[192:195], v[46:49]
	v_mfma_f32_16x16x32_bf16 v[38:41], v[160:163], v[192:195], v[38:41]
	v_mfma_f32_16x16x32_bf16 v[30:33], v[146:149], v[208:211], v[30:33]
	v_mfma_f32_16x16x32_bf16 v[22:25], v[160:163], v[208:211], v[22:25]
	v_mfma_f32_16x16x32_bf16 v[14:17], v[146:149], v[216:219], v[14:17]
	v_mfma_f32_16x16x32_bf16 v[6:9], v[160:163], v[216:219], v[6:9]
	v_mfma_f32_16x16x32_bf16 v[62:65], v[156:159], v[188:191], v[62:65]
	v_mfma_f32_16x16x32_bf16 v[54:57], v[164:167], v[188:191], v[54:57]
	v_mfma_f32_16x16x32_bf16 v[46:49], v[156:159], v[204:207], v[46:49]
	v_mfma_f32_16x16x32_bf16 v[38:41], v[164:167], v[204:207], v[38:41]
	v_mfma_f32_16x16x32_bf16 v[30:33], v[156:159], v[212:215], v[30:33]
	v_mfma_f32_16x16x32_bf16 v[22:25], v[164:167], v[212:215], v[22:25]
	v_mfma_f32_16x16x32_bf16 v[14:17], v[156:159], v[220:223], v[14:17]
	v_mfma_f32_16x16x32_bf16 v[6:9], v[164:167], v[220:223], v[6:9]
	s_setprio 0
	s_setprio 1
	v_mfma_f32_16x16x32_bf16 v[58:61], v[168:171], v[184:187], v[58:61]
	v_mfma_f32_16x16x32_bf16 v[50:53], v[176:179], v[184:187], v[50:53]
	v_mfma_f32_16x16x32_bf16 v[42:45], v[168:171], v[192:195], v[42:45]
	v_mfma_f32_16x16x32_bf16 v[34:37], v[176:179], v[192:195], v[34:37]
	v_mfma_f32_16x16x32_bf16 v[26:29], v[168:171], v[208:211], v[26:29]
	v_mfma_f32_16x16x32_bf16 v[18:21], v[176:179], v[208:211], v[18:21]
	v_mfma_f32_16x16x32_bf16 v[10:13], v[168:171], v[216:219], v[10:13]
	v_mfma_f32_16x16x32_bf16 v[2:5], v[176:179], v[216:219], v[2:5]
	v_mfma_f32_16x16x32_bf16 v[58:61], v[172:175], v[188:191], v[58:61]
	v_mfma_f32_16x16x32_bf16 v[50:53], v[180:183], v[188:191], v[50:53]
	v_mfma_f32_16x16x32_bf16 v[42:45], v[172:175], v[204:207], v[42:45]
	v_mfma_f32_16x16x32_bf16 v[34:37], v[180:183], v[204:207], v[34:37]
	v_mfma_f32_16x16x32_bf16 v[26:29], v[172:175], v[212:215], v[26:29]
	v_mfma_f32_16x16x32_bf16 v[18:21], v[180:183], v[212:215], v[18:21]
	v_mfma_f32_16x16x32_bf16 v[10:13], v[172:175], v[220:223], v[10:13]
	v_mfma_f32_16x16x32_bf16 v[2:5], v[180:183], v[220:223], v[2:5]
	s_barrier
; #define PG8_STAGE(bufoff, gbase, voff) do { _Pragma("unroll") for (int _i = 0; _i < 2; ++_i) \
;         __builtin_amdgcn_global_load_lds((const gunsigned*)((const gchar*)(gbase) + (voff)[_i]), (LAS unsigned*)(lds + (bufoff) + ldsw + _i * 8192), 16, 0, 0); } while (0)
; #define PG8_LDA(dst, b, h) do { _Pragma("unroll") for (int m = 0; m < 4; ++m) _Pragma("unroll") for (int k = 0; k < 2; ++k) dst[m][k] = *(const LAS bf16x8*)(lds + PG8_SA(b, h) + aoff + m * 2048 + k * 1024); } while (0)
; #define PG8_LDB(dst, b, h) do { _Pragma("unroll") for (int n = 0; n < 2; ++n) _Pragma("unroll") for (int k = 0; k < 2; ++k) dst[n][k] = *(const LAS bf16x8*)(lds + PG8_SB(b, h) + boff + n * 2048 + k * 1024); } while (0)
; #define PG8_MMA(ai, bj, At, Bt) do { __builtin_amdgcn_s_setprio(1); _Pragma("unroll") for (int m = 0; m < 4; ++m) _Pragma("unroll") for (int n = 0; n < 2; ++n) _Pragma("unroll") for (int k = 0; k < 2; ++k) \
;         acc[ai][bj][m][n] = __builtin_amdgcn_mfma_f32_16x16x32_bf16(Bt[n][k], At[m][k], acc[ai][bj][m][n], 0, 0, 0); __builtin_amdgcn_s_setprio(0); } while (0)
; #define PG8_WAIT_V(n) asm volatile("s_waitcnt vmcnt(" #n ")" ::: "memory")
; #define PG8_WAIT_L(n) asm volatile("s_waitcnt lgkmcnt(" #n ")" ::: "memory")
; #define PG8_BAR __builtin_amdgcn_s_barrier()
; #define PG8_SCHED __builtin_amdgcn_sched_barrier(0)
; template <class Epi, class Sched>
; __device__ __forceinline__ void gemm_phase(LAS unsigned char* lds, const int tid, const Gemm g, const Sched& S, const Epi& E) {
;     ...
;             PG8_LDB(B0, 1, 0); PG8_LDB(B1, 1, 1); PG8_SCHED; PG8_LDA(At, 1, 0); PG8_STAGE(PG8_SA(0, 1), a2 + hstep, voffA);
;             PG8_WAIT_V(8); PG8_WAIT_L(0); PG8_BAR; PG8_MMA(0, 0, At, B0); PG8_MMA(0, 1, At, B1); PG8_BAR; PG8_SCHED;
;             PG8_LDA(At, 1, 1); PG8_STAGE(PG8_SB(1, 0), b3, voffB); PG8_STAGE(PG8_SB(1, 1), b3 + hstep, voffB); PG8_STAGE(PG8_SA(1, 0), a3, voffA);
;             PG8_WAIT_V(8); PG8_WAIT_L(0); PG8_BAR; PG8_MMA(1, 0, At, B0); PG8_MMA(1, 1, At, B1); PG8_BAR; PG8_SCHED;
;         }
;         if (wr == 0) PG8_BAR;
	s_setprio 0
	s_add_i32 s29, 0, 0x18000
	v_add_u32_e32 v142, s29, v145
	s_add_i32 s30, 0, 0x1c000
	ds_read_b128 v[146:149], v142
	ds_read_b128 v[156:159], v142 offset:1024
	ds_read_b128 v[160:163], v142 offset:2048
	ds_read_b128 v[164:167], v142 offset:3072
	v_add_u32_e32 v142, s30, v145
	ds_read_b128 v[168:171], v142
	ds_read_b128 v[172:175], v142 offset:1024
	ds_read_b128 v[176:179], v142 offset:2048
	ds_read_b128 v[180:183], v142 offset:3072
	s_add_u32 s46, s56, 0x40000
	s_addc_u32 s47, s57, 0
	s_mov_b32 m0, s75
	ds_read_b128 v[184:187], v155 offset:32768
	ds_read_b128 v[188:191], v155 offset:33792
	ds_read_b128 v[192:195], v155 offset:34816
	ds_read_b128 v[204:207], v155 offset:35840
	ds_read_b128 v[208:211], v155 offset:36864
	ds_read_b128 v[212:215], v155 offset:37888
	ds_read_b128 v[216:219], v155 offset:38912
	ds_read_b128 v[220:223], v155 offset:39936
	global_load_lds_dwordx4 v134, s[46:47]
	s_mov_b32 m0, s92
	s_nop 0
	global_load_lds_dwordx4 v132, s[46:47]
	s_waitcnt vmcnt(8)
	s_waitcnt lgkmcnt(0)
	s_barrier
	s_setprio 1
	v_mfma_f32_16x16x32_bf16 v[126:129], v[146:149], v[184:187], v[126:129]
	v_mfma_f32_16x16x32_bf16 v[118:121], v[160:163], v[184:187], v[118:121]
	v_mfma_f32_16x16x32_bf16 v[110:113], v[146:149], v[192:195], v[110:113]
	v_mfma_f32_16x16x32_bf16 v[102:105], v[160:163], v[192:195], v[102:105]
	v_mfma_f32_16x16x32_bf16 v[94:97], v[146:149], v[208:211], v[94:97]
	v_mfma_f32_16x16x32_bf16 v[86:89], v[160:163], v[208:211], v[86:89]
	v_mfma_f32_16x16x32_bf16 v[78:81], v[146:149], v[216:219], v[78:81]
	v_mfma_f32_16x16x32_bf16 v[70:73], v[160:163], v[216:219], v[70:73]
	v_mfma_f32_16x16x32_bf16 v[126:129], v[156:159], v[188:191], v[126:129]
	v_mfma_f32_16x16x32_bf16 v[118:121], v[164:167], v[188:191], v[118:121]
	v_mfma_f32_16x16x32_bf16 v[110:113], v[156:159], v[204:207], v[110:113]
	v_mfma_f32_16x16x32_bf16 v[102:105], v[164:167], v[204:207], v[102:105]
	v_mfma_f32_16x16x32_bf16 v[94:97], v[156:159], v[212:215], v[94:97]
	v_mfma_f32_16x16x32_bf16 v[86:89], v[164:167], v[212:215], v[86:89]
	v_mfma_f32_16x16x32_bf16 v[78:81], v[156:159], v[220:223], v[78:81]
	v_mfma_f32_16x16x32_bf16 v[70:73], v[164:167], v[220:223], v[70:73]
	s_setprio 0
	s_setprio 1
	v_mfma_f32_16x16x32_bf16 v[122:125], v[168:171], v[184:187], v[122:125]
	v_mfma_f32_16x16x32_bf16 v[114:117], v[176:179], v[184:187], v[114:117]
	v_mfma_f32_16x16x32_bf16 v[106:109], v[168:171], v[192:195], v[106:109]
	v_mfma_f32_16x16x32_bf16 v[98:101], v[176:179], v[192:195], v[98:101]
	v_mfma_f32_16x16x32_bf16 v[90:93], v[168:171], v[208:211], v[90:93]
	v_mfma_f32_16x16x32_bf16 v[82:85], v[176:179], v[208:211], v[82:85]
	v_mfma_f32_16x16x32_bf16 v[74:77], v[168:171], v[216:219], v[74:77]
	v_mfma_f32_16x16x32_bf16 v[66:69], v[176:179], v[216:219], v[66:69]
	v_mfma_f32_16x16x32_bf16 v[122:125], v[172:175], v[188:191], v[122:125]
	v_mfma_f32_16x16x32_bf16 v[114:117], v[180:183], v[188:191], v[114:117]
	v_mfma_f32_16x16x32_bf16 v[106:109], v[172:175], v[204:207], v[106:109]
	v_mfma_f32_16x16x32_bf16 v[98:101], v[180:183], v[204:207], v[98:101]
	v_mfma_f32_16x16x32_bf16 v[90:93], v[172:175], v[212:215], v[90:93]
	v_mfma_f32_16x16x32_bf16 v[82:85], v[180:183], v[212:215], v[82:85]
	v_mfma_f32_16x16x32_bf16 v[74:77], v[172:175], v[220:223], v[74:77]
	v_mfma_f32_16x16x32_bf16 v[66:69], v[180:183], v[220:223], v[66:69]
	s_barrier
	s_setprio 0
	s_add_i32 s29, s29, s43
	s_mov_b32 m0, s29
	ds_read_b128 v[184:187], v155 offset:49152
	ds_read_b128 v[188:191], v155 offset:50176
	ds_read_b128 v[192:195], v155 offset:51200
	ds_read_b128 v[204:207], v155 offset:52224
	ds_read_b128 v[208:211], v155 offset:53248
	ds_read_b128 v[212:215], v155 offset:54272
	ds_read_b128 v[216:219], v155 offset:55296
	ds_read_b128 v[220:223], v155 offset:56320
	global_load_lds_dwordx4 v141, s[20:21]
	s_add_i32 m0, s29, 0x2000
	s_add_i32 s29, s30, s43
	global_load_lds_dwordx4 v153, s[20:21]
	s_add_u32 s20, s20, 0x40080
	s_addc_u32 s21, s21, 0
	s_mov_b32 m0, s29
	s_nop 0
	global_load_lds_dwordx4 v0, s[20:21]
	s_add_i32 m0, s29, 0x2000
	s_nop 0
	global_load_lds_dwordx4 v130, s[20:21]
	s_mov_b32 m0, s93
	s_nop 0
	global_load_lds_dwordx4 v201, s[56:57]
	s_mov_b32 m0, s44
	s_nop 0
	global_load_lds_dwordx4 v225, s[56:57]
	s_waitcnt vmcnt(8)
	s_waitcnt lgkmcnt(0)
	s_barrier
	s_setprio 1
	v_mfma_f32_16x16x32_bf16 v[62:65], v[146:149], v[184:187], v[62:65]
	v_mfma_f32_16x16x32_bf16 v[54:57], v[160:163], v[184:187], v[54:57]
	v_mfma_f32_16x16x32_bf16 v[46:49], v[146:149], v[192:195], v[46:49]
	v_mfma_f32_16x16x32_bf16 v[38:41], v[160:163], v[192:195], v[38:41]
	v_mfma_f32_16x16x32_bf16 v[30:33], v[146:149], v[208:211], v[30:33]
	v_mfma_f32_16x16x32_bf16 v[22:25], v[160:163], v[208:211], v[22:25]
	v_mfma_f32_16x16x32_bf16 v[14:17], v[146:149], v[216:219], v[14:17]
	v_mfma_f32_16x16x32_bf16 v[6:9], v[160:163], v[216:219], v[6:9]
	v_mfma_f32_16x16x32_bf16 v[62:65], v[156:159], v[188:191], v[62:65]
	v_mfma_f32_16x16x32_bf16 v[54:57], v[164:167], v[188:191], v[54:57]
	v_mfma_f32_16x16x32_bf16 v[46:49], v[156:159], v[204:207], v[46:49]
	v_mfma_f32_16x16x32_bf16 v[38:41], v[164:167], v[204:207], v[38:41]
	v_mfma_f32_16x16x32_bf16 v[30:33], v[156:159], v[212:215], v[30:33]
	v_mfma_f32_16x16x32_bf16 v[22:25], v[164:167], v[212:215], v[22:25]
	v_mfma_f32_16x16x32_bf16 v[14:17], v[156:159], v[220:223], v[14:17]
	v_mfma_f32_16x16x32_bf16 v[6:9], v[164:167], v[220:223], v[6:9]
	s_setprio 0
	s_setprio 1
	v_mfma_f32_16x16x32_bf16 v[58:61], v[168:171], v[184:187], v[58:61]
	v_mfma_f32_16x16x32_bf16 v[50:53], v[176:179], v[184:187], v[50:53]
	v_mfma_f32_16x16x32_bf16 v[42:45], v[168:171], v[192:195], v[42:45]
	v_mfma_f32_16x16x32_bf16 v[34:37], v[176:179], v[192:195], v[34:37]
	v_mfma_f32_16x16x32_bf16 v[26:29], v[168:171], v[208:211], v[26:29]
	v_mfma_f32_16x16x32_bf16 v[18:21], v[176:179], v[208:211], v[18:21]
	v_mfma_f32_16x16x32_bf16 v[10:13], v[168:171], v[216:219], v[10:13]
	v_mfma_f32_16x16x32_bf16 v[2:5], v[176:179], v[216:219], v[2:5]
	v_mfma_f32_16x16x32_bf16 v[58:61], v[172:175], v[188:191], v[58:61]
	v_mfma_f32_16x16x32_bf16 v[50:53], v[180:183], v[188:191], v[50:53]
	v_mfma_f32_16x16x32_bf16 v[42:45], v[172:175], v[204:207], v[42:45]
	v_mfma_f32_16x16x32_bf16 v[34:37], v[180:183], v[204:207], v[34:37]
	v_mfma_f32_16x16x32_bf16 v[26:29], v[172:175], v[212:215], v[26:29]
	v_mfma_f32_16x16x32_bf16 v[18:21], v[180:183], v[212:215], v[18:21]
	v_mfma_f32_16x16x32_bf16 v[10:13], v[172:175], v[220:223], v[10:13]
	v_mfma_f32_16x16x32_bf16 v[2:5], v[180:183], v[220:223], v[2:5]
	s_barrier
	s_setprio 0
	s_add_i32 s31, s31, 2
	s_add_u32 s23, s23, 0x100
	s_addc_u32 s24, s24, 0
	s_add_u32 s16, s16, 0x100
	s_addc_u32 s17, s17, 0
	s_cmp_gt_u32 s31, 13
	s_cbranch_scc0 .LBB0_369
	s_and_b64 vcc, exec, s[6:7]
	s_cbranch_vccz .LBB0_372
	s_barrier

; #define PG8_STAGE(bufoff, gbase, voff) do { _Pragma("unroll") for (int _i = 0; _i < 2; ++_i) \
;         __builtin_amdgcn_global_load_lds((const gunsigned*)((const gchar*)(gbase) + (voff)[_i]), (LAS unsigned*)(lds + (bufoff) + ldsw + _i * 8192), 16, 0, 0); } while (0)
; #define PG8_LDA(dst, b, h) do { _Pragma("unroll") for (int m = 0; m < 4; ++m) _Pragma("unroll") for (int k = 0; k < 2; ++k) dst[m][k] = *(const LAS bf16x8*)(lds + PG8_SA(b, h) + aoff + m * 2048 + k * 1024); } while (0)
; #define PG8_LDB(dst, b, h) do { _Pragma("unroll") for (int n = 0; n < 2; ++n) _Pragma("unroll") for (int k = 0; k < 2; ++k) dst[n][k] = *(const LAS bf16x8*)(lds + PG8_SB(b, h) + boff + n * 2048 + k * 1024); } while (0)
; #define PG8_MMA(ai, bj, At, Bt) do { __builtin_amdgcn_s_setprio(1); _Pragma("unroll") for (int m = 0; m < 4; ++m) _Pragma("unroll") for (int n = 0; n < 2; ++n) _Pragma("unroll") for (int k = 0; k < 2; ++k) \
;         acc[ai][bj][m][n] = __builtin_amdgcn_mfma_f32_16x16x32_bf16(Bt[n][k], At[m][k], acc[ai][bj][m][n], 0, 0, 0); __builtin_amdgcn_s_setprio(0); } while (0)
; #define PG8_WAIT_V(n) asm volatile("s_waitcnt vmcnt(" #n ")" ::: "memory")
; #define PG8_WAIT_L(n) asm volatile("s_waitcnt lgkmcnt(" #n ")" ::: "memory")
; #define PG8_BAR __builtin_amdgcn_s_barrier()
; #define PG8_SCHED __builtin_amdgcn_sched_barrier(0)
; template <class Epi, class Sched>
; __device__ __forceinline__ void gemm_phase(LAS unsigned char* lds, const int tid, const Gemm g, const Sched& S, const Epi& E) {
;     ...
;             const bool last = (t == nt - 2);
;             const gchar* a1 = cA + (size_t)(t + 1) * kstep;
;             const gchar* a2 = last ? nA : cA + (size_t)(t + 2) * kstep; const gchar* b2 = last ? nB : cB + (size_t)(t + 2) * kstep;
;             const gchar* a3 = a2 + kstep; const gchar* b3 = b2 + kstep;
;             PG8_LDB(B0, 0, 0); PG8_LDB(B1, 0, 1); PG8_SCHED; PG8_LDA(At, 0, 0); PG8_STAGE(PG8_SA(1, 1), a1 + hstep, voffA);
;             PG8_WAIT_V(8); PG8_WAIT_L(0); PG8_BAR; PG8_MMA(0, 0, At, B0); PG8_MMA(0, 1, At, B1); PG8_BAR; PG8_SCHED;
;             PG8_LDA(At, 0, 1); PG8_STAGE(PG8_SB(0, 0), b2, voffB); PG8_STAGE(PG8_SB(0, 1), b2 + hstep, voffB); PG8_STAGE(PG8_SA(0, 0), a2, voffA);
;             PG8_WAIT_V(8); PG8_WAIT_L(0); PG8_BAR; PG8_MMA(1, 0, At, B0); PG8_MMA(1, 1, At, B1); PG8_BAR; PG8_SCHED;
.LBB0_397:
	s_add_u32 s20, s92, 0xfffc0080
	s_addc_u32 s21, s93, -1
	s_add_i32 s29, 0, 0x10000
	s_cmp_eq_u32 s53, 12
	s_cselect_b32 s73, s1, s21
	s_cselect_b32 s72, s31, s20
	s_cselect_b32 s21, s17, s52
	s_cselect_b32 s20, s50, s51
	s_add_i32 s30, 0, 0x14000
	v_add_u32_e32 v142, s29, v177
	v_add_u32_e32 v168, s30, v177
	ds_read_b128 v[130:133], v142
	ds_read_b128 v[134:137], v142 offset:1024
	ds_read_b128 v[138:141], v142 offset:2048
	ds_read_b128 v[142:145], v142 offset:3072
	ds_read_b128 v[146:149], v168
	ds_read_b128 v[150:153], v168 offset:1024
	ds_read_b128 v[164:167], v168 offset:2048
	ds_read_b128 v[168:171], v168 offset:3072
	s_add_i32 m0, s43, 0xc000
	ds_read_b128 v[172:175], v181
	ds_read_b128 v[182:185], v181 offset:1024
	ds_read_b128 v[186:189], v181 offset:2048
	ds_read_b128 v[190:193], v181 offset:3072
	ds_read_b128 v[204:207], v181 offset:4096
	ds_read_b128 v[208:211], v181 offset:5120
	ds_read_b128 v[212:215], v181 offset:6144
	ds_read_b128 v[216:219], v181 offset:7168
	global_load_lds_dwordx4 v162, s[92:93]
	s_add_i32 m0, s43, 0xe000
	s_nop 0
	global_load_lds_dwordx4 v160, s[92:93]
	s_waitcnt vmcnt(8)
	s_waitcnt lgkmcnt(0)
	s_barrier
	s_setprio 1
	v_mfma_f32_16x16x32_bf16 v[126:129], v[130:133], v[172:175], v[126:129]
	v_mfma_f32_16x16x32_bf16 v[122:125], v[138:141], v[172:175], v[122:125]
	v_mfma_f32_16x16x32_bf16 v[110:113], v[130:133], v[186:189], v[110:113]
	v_mfma_f32_16x16x32_bf16 v[106:109], v[138:141], v[186:189], v[106:109]
	v_mfma_f32_16x16x32_bf16 v[94:97], v[130:133], v[204:207], v[94:97]
	v_mfma_f32_16x16x32_bf16 v[90:93], v[138:141], v[204:207], v[90:93]
	v_mfma_f32_16x16x32_bf16 v[78:81], v[130:133], v[212:215], v[78:81]
	v_mfma_f32_16x16x32_bf16 v[74:77], v[138:141], v[212:215], v[74:77]
	v_mfma_f32_16x16x32_bf16 v[126:129], v[134:137], v[182:185], v[126:129]
	v_mfma_f32_16x16x32_bf16 v[122:125], v[142:145], v[182:185], v[122:125]
	v_mfma_f32_16x16x32_bf16 v[110:113], v[134:137], v[190:193], v[110:113]
	v_mfma_f32_16x16x32_bf16 v[106:109], v[142:145], v[190:193], v[106:109]
	v_mfma_f32_16x16x32_bf16 v[94:97], v[134:137], v[208:211], v[94:97]
	v_mfma_f32_16x16x32_bf16 v[90:93], v[142:145], v[208:211], v[90:93]
	v_mfma_f32_16x16x32_bf16 v[78:81], v[134:137], v[216:219], v[78:81]
	v_mfma_f32_16x16x32_bf16 v[74:77], v[142:145], v[216:219], v[74:77]
	s_setprio 0
	s_setprio 1
	v_mfma_f32_16x16x32_bf16 v[118:121], v[146:149], v[172:175], v[118:121]
	v_mfma_f32_16x16x32_bf16 v[114:117], v[164:167], v[172:175], v[114:117]
	v_mfma_f32_16x16x32_bf16 v[102:105], v[146:149], v[186:189], v[102:105]
	v_mfma_f32_16x16x32_bf16 v[98:101], v[164:167], v[186:189], v[98:101]
	v_mfma_f32_16x16x32_bf16 v[86:89], v[146:149], v[204:207], v[86:89]
	v_mfma_f32_16x16x32_bf16 v[82:85], v[164:167], v[204:207], v[82:85]
	v_mfma_f32_16x16x32_bf16 v[70:73], v[146:149], v[212:215], v[70:73]
	v_mfma_f32_16x16x32_bf16 v[66:69], v[164:167], v[212:215], v[66:69]
	v_mfma_f32_16x16x32_bf16 v[118:121], v[150:153], v[182:185], v[118:121]
	v_mfma_f32_16x16x32_bf16 v[114:117], v[168:171], v[182:185], v[114:117]
	v_mfma_f32_16x16x32_bf16 v[102:105], v[150:153], v[190:193], v[102:105]
	v_mfma_f32_16x16x32_bf16 v[98:101], v[168:171], v[190:193], v[98:101]
	v_mfma_f32_16x16x32_bf16 v[86:89], v[150:153], v[208:211], v[86:89]
	v_mfma_f32_16x16x32_bf16 v[82:85], v[168:171], v[208:211], v[82:85]
	v_mfma_f32_16x16x32_bf16 v[70:73], v[150:153], v[216:219], v[70:73]
	v_mfma_f32_16x16x32_bf16 v[66:69], v[168:171], v[216:219], v[66:69]
	s_barrier
	s_setprio 0
	s_add_i32 s29, s29, s15
	s_mov_b32 m0, s29
	ds_read_b128 v[172:175], v181 offset:16384
	ds_read_b128 v[182:185], v181 offset:17408
	ds_read_b128 v[186:189], v181 offset:18432
	ds_read_b128 v[190:193], v181 offset:19456
	ds_read_b128 v[204:207], v181 offset:20480
	ds_read_b128 v[208:211], v181 offset:21504
	ds_read_b128 v[212:215], v181 offset:22528
	ds_read_b128 v[216:219], v181 offset:23552
	global_load_lds_dwordx4 v0, s[20:21]
	s_add_i32 m0, s29, 0x2000
	s_add_u32 s54, s20, 0x40000
	s_addc_u32 s55, s21, 0
	s_add_i32 s29, s30, s15
	global_load_lds_dwordx4 v158, s[20:21]
	s_mov_b32 m0, s29
	s_nop 0
	global_load_lds_dwordx4 v0, s[54:55]
	s_add_i32 m0, s29, 0x2000
	s_nop 0
	global_load_lds_dwordx4 v158, s[54:55]
	s_mov_b32 m0, s43
	s_nop 0
	global_load_lds_dwordx4 v154, s[72:73]
	s_mov_b32 m0, s44
	s_nop 0
	global_load_lds_dwordx4 v156, s[72:73]
	s_waitcnt vmcnt(8)
	s_waitcnt lgkmcnt(0)
	s_barrier
	s_setprio 1
	v_mfma_f32_16x16x32_bf16 v[62:65], v[130:133], v[172:175], v[62:65]
	v_mfma_f32_16x16x32_bf16 v[58:61], v[138:141], v[172:175], v[58:61]
	v_mfma_f32_16x16x32_bf16 v[46:49], v[130:133], v[186:189], v[46:49]
	v_mfma_f32_16x16x32_bf16 v[42:45], v[138:141], v[186:189], v[42:45]
	v_mfma_f32_16x16x32_bf16 v[30:33], v[130:133], v[204:207], v[30:33]
	v_mfma_f32_16x16x32_bf16 v[26:29], v[138:141], v[204:207], v[26:29]
	v_mfma_f32_16x16x32_bf16 v[14:17], v[130:133], v[212:215], v[14:17]
	v_mfma_f32_16x16x32_bf16 v[10:13], v[138:141], v[212:215], v[10:13]
	v_mfma_f32_16x16x32_bf16 v[62:65], v[134:137], v[182:185], v[62:65]
	v_mfma_f32_16x16x32_bf16 v[58:61], v[142:145], v[182:185], v[58:61]
	v_mfma_f32_16x16x32_bf16 v[46:49], v[134:137], v[190:193], v[46:49]
	v_mfma_f32_16x16x32_bf16 v[42:45], v[142:145], v[190:193], v[42:45]
	v_mfma_f32_16x16x32_bf16 v[30:33], v[134:137], v[208:211], v[30:33]
	v_mfma_f32_16x16x32_bf16 v[26:29], v[142:145], v[208:211], v[26:29]
	v_mfma_f32_16x16x32_bf16 v[14:17], v[134:137], v[216:219], v[14:17]
	v_mfma_f32_16x16x32_bf16 v[10:13], v[142:145], v[216:219], v[10:13]
	s_setprio 0
	s_setprio 1
	v_mfma_f32_16x16x32_bf16 v[54:57], v[146:149], v[172:175], v[54:57]
	v_mfma_f32_16x16x32_bf16 v[50:53], v[164:167], v[172:175], v[50:53]
	v_mfma_f32_16x16x32_bf16 v[38:41], v[146:149], v[186:189], v[38:41]
	v_mfma_f32_16x16x32_bf16 v[34:37], v[164:167], v[186:189], v[34:37]
	v_mfma_f32_16x16x32_bf16 v[22:25], v[146:149], v[204:207], v[22:25]
	v_mfma_f32_16x16x32_bf16 v[18:21], v[164:167], v[204:207], v[18:21]
	v_mfma_f32_16x16x32_bf16 v[6:9], v[146:149], v[212:215], v[6:9]
	v_mfma_f32_16x16x32_bf16 v[2:5], v[164:167], v[212:215], v[2:5]
	v_mfma_f32_16x16x32_bf16 v[54:57], v[150:153], v[182:185], v[54:57]
	v_mfma_f32_16x16x32_bf16 v[50:53], v[168:171], v[182:185], v[50:53]
	v_mfma_f32_16x16x32_bf16 v[38:41], v[150:153], v[190:193], v[38:41]
	v_mfma_f32_16x16x32_bf16 v[34:37], v[168:171], v[190:193], v[34:37]
	v_mfma_f32_16x16x32_bf16 v[22:25], v[150:153], v[208:211], v[22:25]
	v_mfma_f32_16x16x32_bf16 v[18:21], v[168:171], v[208:211], v[18:21]
	v_mfma_f32_16x16x32_bf16 v[6:9], v[150:153], v[216:219], v[6:9]
	v_mfma_f32_16x16x32_bf16 v[2:5], v[168:171], v[216:219], v[2:5]
	s_barrier
; #define PG8_STAGE(bufoff, gbase, voff) do { _Pragma("unroll") for (int _i = 0; _i < 2; ++_i) \
;         __builtin_amdgcn_global_load_lds((const gunsigned*)((const gchar*)(gbase) + (voff)[_i]), (LAS unsigned*)(lds + (bufoff) + ldsw + _i * 8192), 16, 0, 0); } while (0)
; #define PG8_LDA(dst, b, h) do { _Pragma("unroll") for (int m = 0; m < 4; ++m) _Pragma("unroll") for (int k = 0; k < 2; ++k) dst[m][k] = *(const LAS bf16x8*)(lds + PG8_SA(b, h) + aoff + m * 2048 + k * 1024); } while (0)
; #define PG8_LDB(dst, b, h) do { _Pragma("unroll") for (int n = 0; n < 2; ++n) _Pragma("unroll") for (int k = 0; k < 2; ++k) dst[n][k] = *(const LAS bf16x8*)(lds + PG8_SB(b, h) + boff + n * 2048 + k * 1024); } while (0)
; #define PG8_MMA(ai, bj, At, Bt) do { __builtin_amdgcn_s_setprio(1); _Pragma("unroll") for (int m = 0; m < 4; ++m) _Pragma("unroll") for (int n = 0; n < 2; ++n) _Pragma("unroll") for (int k = 0; k < 2; ++k) \
;         acc[ai][bj][m][n] = __builtin_amdgcn_mfma_f32_16x16x32_bf16(Bt[n][k], At[m][k], acc[ai][bj][m][n], 0, 0, 0); __builtin_amdgcn_s_setprio(0); } while (0)
; #define PG8_WAIT_V(n) asm volatile("s_waitcnt vmcnt(" #n ")" ::: "memory")
; #define PG8_WAIT_L(n) asm volatile("s_waitcnt lgkmcnt(" #n ")" ::: "memory")
; #define PG8_BAR __builtin_amdgcn_s_barrier()
; #define PG8_SCHED __builtin_amdgcn_sched_barrier(0)
; template <class Epi, class Sched>
; __device__ __forceinline__ void gemm_phase(LAS unsigned char* lds, const int tid, const Gemm g, const Sched& S, const Epi& E) {
;     ...
;             PG8_LDB(B0, 1, 0); PG8_LDB(B1, 1, 1); PG8_SCHED; PG8_LDA(At, 1, 0); PG8_STAGE(PG8_SA(0, 1), a2 + hstep, voffA);
;             PG8_WAIT_V(8); PG8_WAIT_L(0); PG8_BAR; PG8_MMA(0, 0, At, B0); PG8_MMA(0, 1, At, B1); PG8_BAR; PG8_SCHED;
;             PG8_LDA(At, 1, 1); PG8_STAGE(PG8_SB(1, 0), b3, voffB); PG8_STAGE(PG8_SB(1, 1), b3 + hstep, voffB); PG8_STAGE(PG8_SA(1, 0), a3, voffA);
;             PG8_WAIT_V(8); PG8_WAIT_L(0); PG8_BAR; PG8_MMA(1, 0, At, B0); PG8_MMA(1, 1, At, B1); PG8_BAR; PG8_SCHED;
;         }
;         if (wr == 0) PG8_BAR;
	s_setprio 0
	s_add_i32 s29, 0, 0x18000
	s_add_i32 s30, 0, 0x1c000
	v_add_u32_e32 v142, s29, v177
	v_add_u32_e32 v168, s30, v177
	ds_read_b128 v[130:133], v142
	ds_read_b128 v[134:137], v142 offset:1024
	ds_read_b128 v[138:141], v142 offset:2048
	ds_read_b128 v[142:145], v142 offset:3072
	ds_read_b128 v[146:149], v168
	ds_read_b128 v[150:153], v168 offset:1024
	ds_read_b128 v[164:167], v168 offset:2048
	ds_read_b128 v[168:171], v168 offset:3072
	s_add_u32 s54, s72, 0x40000
	s_addc_u32 s55, s73, 0
	s_mov_b32 m0, s45
	ds_read_b128 v[172:175], v181 offset:32768
	ds_read_b128 v[182:185], v181 offset:33792
	ds_read_b128 v[186:189], v181 offset:34816
	ds_read_b128 v[190:193], v181 offset:35840
	ds_read_b128 v[204:207], v181 offset:36864
	ds_read_b128 v[208:211], v181 offset:37888
	ds_read_b128 v[212:215], v181 offset:38912
	ds_read_b128 v[216:219], v181 offset:39936
	global_load_lds_dwordx4 v154, s[54:55]
	s_mov_b32 m0, s46
	s_nop 0
	global_load_lds_dwordx4 v156, s[54:55]
	s_waitcnt vmcnt(8)
	s_waitcnt lgkmcnt(0)
	s_barrier
	s_setprio 1
	v_mfma_f32_16x16x32_bf16 v[126:129], v[130:133], v[172:175], v[126:129]
	v_mfma_f32_16x16x32_bf16 v[122:125], v[138:141], v[172:175], v[122:125]
	v_mfma_f32_16x16x32_bf16 v[110:113], v[130:133], v[186:189], v[110:113]
	v_mfma_f32_16x16x32_bf16 v[106:109], v[138:141], v[186:189], v[106:109]
	v_mfma_f32_16x16x32_bf16 v[94:97], v[130:133], v[204:207], v[94:97]
	v_mfma_f32_16x16x32_bf16 v[90:93], v[138:141], v[204:207], v[90:93]
	v_mfma_f32_16x16x32_bf16 v[78:81], v[130:133], v[212:215], v[78:81]
	v_mfma_f32_16x16x32_bf16 v[74:77], v[138:141], v[212:215], v[74:77]
	v_mfma_f32_16x16x32_bf16 v[126:129], v[134:137], v[182:185], v[126:129]
	v_mfma_f32_16x16x32_bf16 v[122:125], v[142:145], v[182:185], v[122:125]
	v_mfma_f32_16x16x32_bf16 v[110:113], v[134:137], v[190:193], v[110:113]
	v_mfma_f32_16x16x32_bf16 v[106:109], v[142:145], v[190:193], v[106:109]
	v_mfma_f32_16x16x32_bf16 v[94:97], v[134:137], v[208:211], v[94:97]
	v_mfma_f32_16x16x32_bf16 v[90:93], v[142:145], v[208:211], v[90:93]
	v_mfma_f32_16x16x32_bf16 v[78:81], v[134:137], v[216:219], v[78:81]
	v_mfma_f32_16x16x32_bf16 v[74:77], v[142:145], v[216:219], v[74:77]
	s_setprio 0
	s_setprio 1
	v_mfma_f32_16x16x32_bf16 v[118:121], v[146:149], v[172:175], v[118:121]
	v_mfma_f32_16x16x32_bf16 v[114:117], v[164:167], v[172:175], v[114:117]
	v_mfma_f32_16x16x32_bf16 v[102:105], v[146:149], v[186:189], v[102:105]
	v_mfma_f32_16x16x32_bf16 v[98:101], v[164:167], v[186:189], v[98:101]
	v_mfma_f32_16x16x32_bf16 v[86:89], v[146:149], v[204:207], v[86:89]
	v_mfma_f32_16x16x32_bf16 v[82:85], v[164:167], v[204:207], v[82:85]
	v_mfma_f32_16x16x32_bf16 v[70:73], v[146:149], v[212:215], v[70:73]
	v_mfma_f32_16x16x32_bf16 v[66:69], v[164:167], v[212:215], v[66:69]
	v_mfma_f32_16x16x32_bf16 v[118:121], v[150:153], v[182:185], v[118:121]
	v_mfma_f32_16x16x32_bf16 v[114:117], v[168:171], v[182:185], v[114:117]
	v_mfma_f32_16x16x32_bf16 v[102:105], v[150:153], v[190:193], v[102:105]
	v_mfma_f32_16x16x32_bf16 v[98:101], v[168:171], v[190:193], v[98:101]
	v_mfma_f32_16x16x32_bf16 v[86:89], v[150:153], v[208:211], v[86:89]
	v_mfma_f32_16x16x32_bf16 v[82:85], v[168:171], v[208:211], v[82:85]
	v_mfma_f32_16x16x32_bf16 v[70:73], v[150:153], v[216:219], v[70:73]
	v_mfma_f32_16x16x32_bf16 v[66:69], v[168:171], v[216:219], v[66:69]
	s_barrier
	s_setprio 0
	s_add_i32 s29, s29, s15
	s_mov_b32 m0, s29
	ds_read_b128 v[172:175], v181 offset:49152
	ds_read_b128 v[182:185], v181 offset:50176
	ds_read_b128 v[186:189], v181 offset:51200
	ds_read_b128 v[190:193], v181 offset:52224
	ds_read_b128 v[204:207], v181 offset:53248
	ds_read_b128 v[208:211], v181 offset:54272
	ds_read_b128 v[212:215], v181 offset:55296
	ds_read_b128 v[216:219], v181 offset:56320
	global_load_lds_dwordx4 v195, s[20:21]
	s_add_i32 m0, s29, 0x2000
	s_add_i32 s29, s30, s15
	global_load_lds_dwordx4 v201, s[20:21]
	s_add_u32 s20, s20, 0x40080
	s_addc_u32 s21, s21, 0
	s_mov_b32 m0, s29
	s_nop 0
	global_load_lds_dwordx4 v0, s[20:21]
	s_add_i32 m0, s29, 0x2000
	s_nop 0
	global_load_lds_dwordx4 v158, s[20:21]
	s_mov_b32 m0, s12
	s_nop 0
	global_load_lds_dwordx4 v221, s[72:73]
	s_mov_b32 m0, s47
	s_nop 0
	global_load_lds_dwordx4 v223, s[72:73]
	s_waitcnt vmcnt(8)
	s_waitcnt lgkmcnt(0)
	s_barrier
	s_setprio 1
	v_mfma_f32_16x16x32_bf16 v[62:65], v[130:133], v[172:175], v[62:65]
	v_mfma_f32_16x16x32_bf16 v[58:61], v[138:141], v[172:175], v[58:61]
	v_mfma_f32_16x16x32_bf16 v[46:49], v[130:133], v[186:189], v[46:49]
	v_mfma_f32_16x16x32_bf16 v[42:45], v[138:141], v[186:189], v[42:45]
	v_mfma_f32_16x16x32_bf16 v[30:33], v[130:133], v[204:207], v[30:33]
	v_mfma_f32_16x16x32_bf16 v[26:29], v[138:141], v[204:207], v[26:29]
	v_mfma_f32_16x16x32_bf16 v[14:17], v[130:133], v[212:215], v[14:17]
	v_mfma_f32_16x16x32_bf16 v[10:13], v[138:141], v[212:215], v[10:13]
	v_mfma_f32_16x16x32_bf16 v[62:65], v[134:137], v[182:185], v[62:65]
	v_mfma_f32_16x16x32_bf16 v[58:61], v[142:145], v[182:185], v[58:61]
	v_mfma_f32_16x16x32_bf16 v[46:49], v[134:137], v[190:193], v[46:49]
	v_mfma_f32_16x16x32_bf16 v[42:45], v[142:145], v[190:193], v[42:45]
	v_mfma_f32_16x16x32_bf16 v[30:33], v[134:137], v[208:211], v[30:33]
	v_mfma_f32_16x16x32_bf16 v[26:29], v[142:145], v[208:211], v[26:29]
	v_mfma_f32_16x16x32_bf16 v[14:17], v[134:137], v[216:219], v[14:17]
	v_mfma_f32_16x16x32_bf16 v[10:13], v[142:145], v[216:219], v[10:13]
	s_setprio 0
	s_setprio 1
	v_mfma_f32_16x16x32_bf16 v[54:57], v[146:149], v[172:175], v[54:57]
	v_mfma_f32_16x16x32_bf16 v[50:53], v[164:167], v[172:175], v[50:53]
	v_mfma_f32_16x16x32_bf16 v[38:41], v[146:149], v[186:189], v[38:41]
	v_mfma_f32_16x16x32_bf16 v[34:37], v[164:167], v[186:189], v[34:37]
	v_mfma_f32_16x16x32_bf16 v[22:25], v[146:149], v[204:207], v[22:25]
	v_mfma_f32_16x16x32_bf16 v[18:21], v[164:167], v[204:207], v[18:21]
	v_mfma_f32_16x16x32_bf16 v[6:9], v[146:149], v[212:215], v[6:9]
	v_mfma_f32_16x16x32_bf16 v[2:5], v[164:167], v[212:215], v[2:5]
	v_mfma_f32_16x16x32_bf16 v[54:57], v[150:153], v[182:185], v[54:57]
	v_mfma_f32_16x16x32_bf16 v[50:53], v[168:171], v[182:185], v[50:53]
	v_mfma_f32_16x16x32_bf16 v[38:41], v[150:153], v[190:193], v[38:41]
	v_mfma_f32_16x16x32_bf16 v[34:37], v[168:171], v[190:193], v[34:37]
	v_mfma_f32_16x16x32_bf16 v[22:25], v[150:153], v[208:211], v[22:25]
	v_mfma_f32_16x16x32_bf16 v[18:21], v[168:171], v[208:211], v[18:21]
	v_mfma_f32_16x16x32_bf16 v[6:9], v[150:153], v[216:219], v[6:9]
	v_mfma_f32_16x16x32_bf16 v[2:5], v[168:171], v[216:219], v[2:5]
	s_barrier
	s_setprio 0
	s_add_i32 s53, s53, 2
	s_add_u32 s51, s51, 0x100
	s_addc_u32 s52, s52, 0
	s_add_u32 s92, s92, 0x100
	s_addc_u32 s93, s93, 0
	s_cmp_gt_u32 s53, 13
	s_cbranch_scc0 .LBB0_397
	s_and_b64 vcc, exec, s[10:11]
	s_cbranch_vccz .LBB0_400
	s_barrier

; #define PG8_STAGE(bufoff, gbase, voff) do { _Pragma("unroll") for (int _i = 0; _i < 2; ++_i) \
;         __builtin_amdgcn_global_load_lds((const gunsigned*)((const gchar*)(gbase) + (voff)[_i]), (LAS unsigned*)(lds + (bufoff) + ldsw + _i * 8192), 16, 0, 0); } while (0)
; #define PG8_LDA(dst, b, h) do { _Pragma("unroll") for (int m = 0; m < 4; ++m) _Pragma("unroll") for (int k = 0; k < 2; ++k) dst[m][k] = *(const LAS bf16x8*)(lds + PG8_SA(b, h) + aoff + m * 2048 + k * 1024); } while (0)
; #define PG8_LDB(dst, b, h) do { _Pragma("unroll") for (int n = 0; n < 2; ++n) _Pragma("unroll") for (int k = 0; k < 2; ++k) dst[n][k] = *(const LAS bf16x8*)(lds + PG8_SB(b, h) + boff + n * 2048 + k * 1024); } while (0)
; #define PG8_MMA(ai, bj, At, Bt) do { __builtin_amdgcn_s_setprio(1); _Pragma("unroll") for (int m = 0; m < 4; ++m) _Pragma("unroll") for (int n = 0; n < 2; ++n) _Pragma("unroll") for (int k = 0; k < 2; ++k) \
;         acc[ai][bj][m][n] = __builtin_amdgcn_mfma_f32_16x16x32_bf16(Bt[n][k], At[m][k], acc[ai][bj][m][n], 0, 0, 0); __builtin_amdgcn_s_setprio(0); } while (0)
; #define PG8_WAIT_V(n) asm volatile("s_waitcnt vmcnt(" #n ")" ::: "memory")
; #define PG8_WAIT_L(n) asm volatile("s_waitcnt lgkmcnt(" #n ")" ::: "memory")
; #define PG8_BAR __builtin_amdgcn_s_barrier()
; #define PG8_SCHED __builtin_amdgcn_sched_barrier(0)
; template <class Epi, class Sched>
; __device__ __forceinline__ void gemm_phase(LAS unsigned char* lds, const int tid, const Gemm g, const Sched& S, const Epi& E) {
;     ...
;             const bool last = (t == nt - 2);
;             const gchar* a1 = cA + (size_t)(t + 1) * kstep;
;             const gchar* a2 = last ? nA : cA + (size_t)(t + 2) * kstep; const gchar* b2 = last ? nB : cB + (size_t)(t + 2) * kstep;
;             const gchar* a3 = a2 + kstep; const gchar* b3 = b2 + kstep;
;             PG8_LDB(B0, 0, 0); PG8_LDB(B1, 0, 1); PG8_SCHED; PG8_LDA(At, 0, 0); PG8_STAGE(PG8_SA(1, 1), a1 + hstep, voffA);
;             PG8_WAIT_V(8); PG8_WAIT_L(0); PG8_BAR; PG8_MMA(0, 0, At, B0); PG8_MMA(0, 1, At, B1); PG8_BAR; PG8_SCHED;
;             PG8_LDA(At, 0, 1); PG8_STAGE(PG8_SB(0, 0), b2, voffB); PG8_STAGE(PG8_SB(0, 1), b2 + hstep, voffB); PG8_STAGE(PG8_SA(0, 0), a2, voffA);
;             PG8_WAIT_V(8); PG8_WAIT_L(0); PG8_BAR; PG8_MMA(1, 0, At, B0); PG8_MMA(1, 1, At, B1); PG8_BAR; PG8_SCHED;
.LBB0_444:
	s_add_u32 s20, s16, 0xfffe0080
	s_addc_u32 s21, s17, -1
	s_add_i32 s29, 0, 0x10000
	s_cmp_eq_u32 s51, 4
	s_cselect_b32 s73, s1, s21
	s_cselect_b32 s72, s5, s20
	v_add_u32_e32 v122, s29, v242
	s_cselect_b32 s21, s15, s31
	s_cselect_b32 s20, s23, s24
	s_add_i32 s30, 0, 0x14000
	ds_read_b128 v[132:135], v122
	ds_read_b128 v[136:139], v122 offset:1024
	ds_read_b128 v[140:143], v122 offset:2048
	ds_read_b128 v[144:147], v122 offset:3072
	v_add_u32_e32 v122, s30, v242
	ds_read_b128 v[148:151], v122
	ds_read_b128 v[152:155], v122 offset:1024
	ds_read_b128 v[156:159], v122 offset:2048
	ds_read_b128 v[160:163], v122 offset:3072
	s_add_i32 m0, s93, 0xc000
	ds_read_b128 v[164:167], v244
	ds_read_b128 v[168:171], v244 offset:1024
	ds_read_b128 v[172:175], v244 offset:2048
	ds_read_b128 v[176:179], v244 offset:3072
	ds_read_b128 v[180:183], v244 offset:4096
	ds_read_b128 v[184:187], v244 offset:5120
	ds_read_b128 v[188:191], v244 offset:6144
	ds_read_b128 v[192:195], v244 offset:7168
	global_load_lds_dwordx4 v212, s[16:17]
	s_add_i32 m0, s93, 0xe000
	s_nop 0
	global_load_lds_dwordx4 v210, s[16:17]
	s_waitcnt vmcnt(8)
	s_waitcnt lgkmcnt(0)
	s_barrier
	s_setprio 1
	v_mfma_f32_16x16x32_bf16 v[128:131], v[132:135], v[164:167], v[128:131]
	v_mfma_f32_16x16x32_bf16 v[122:125], v[140:143], v[164:167], v[124:127]
	v_mfma_f32_16x16x32_bf16 v[110:113], v[132:135], v[172:175], v[110:113]
	v_mfma_f32_16x16x32_bf16 v[106:109], v[140:143], v[172:175], v[106:109]
	v_mfma_f32_16x16x32_bf16 v[94:97], v[132:135], v[180:183], v[94:97]
	v_mfma_f32_16x16x32_bf16 v[90:93], v[140:143], v[180:183], v[90:93]
	v_mfma_f32_16x16x32_bf16 v[78:81], v[132:135], v[188:191], v[78:81]
	v_mfma_f32_16x16x32_bf16 v[74:77], v[140:143], v[188:191], v[74:77]
	v_mfma_f32_16x16x32_bf16 v[128:131], v[136:139], v[168:171], v[128:131]
	v_mfma_f32_16x16x32_bf16 v[122:125], v[144:147], v[168:171], v[122:125]
	v_mfma_f32_16x16x32_bf16 v[110:113], v[136:139], v[176:179], v[110:113]
	v_mfma_f32_16x16x32_bf16 v[106:109], v[144:147], v[176:179], v[106:109]
	v_mfma_f32_16x16x32_bf16 v[94:97], v[136:139], v[184:187], v[94:97]
	v_mfma_f32_16x16x32_bf16 v[90:93], v[144:147], v[184:187], v[90:93]
	v_mfma_f32_16x16x32_bf16 v[78:81], v[136:139], v[192:195], v[78:81]
	v_mfma_f32_16x16x32_bf16 v[74:77], v[144:147], v[192:195], v[74:77]
	s_setprio 0
	s_setprio 1
	v_mfma_f32_16x16x32_bf16 v[118:121], v[148:151], v[164:167], v[118:121]
	v_mfma_f32_16x16x32_bf16 v[114:117], v[156:159], v[164:167], v[114:117]
	v_mfma_f32_16x16x32_bf16 v[102:105], v[148:151], v[172:175], v[102:105]
	v_mfma_f32_16x16x32_bf16 v[98:101], v[156:159], v[172:175], v[98:101]
	v_mfma_f32_16x16x32_bf16 v[86:89], v[148:151], v[180:183], v[86:89]
	v_mfma_f32_16x16x32_bf16 v[82:85], v[156:159], v[180:183], v[82:85]
	v_mfma_f32_16x16x32_bf16 v[70:73], v[148:151], v[188:191], v[70:73]
	v_mfma_f32_16x16x32_bf16 v[66:69], v[156:159], v[188:191], v[66:69]
	v_mfma_f32_16x16x32_bf16 v[118:121], v[152:155], v[168:171], v[118:121]
	v_mfma_f32_16x16x32_bf16 v[114:117], v[160:163], v[168:171], v[114:117]
	v_mfma_f32_16x16x32_bf16 v[102:105], v[152:155], v[176:179], v[102:105]
	v_mfma_f32_16x16x32_bf16 v[98:101], v[160:163], v[176:179], v[98:101]
	v_mfma_f32_16x16x32_bf16 v[86:89], v[152:155], v[184:187], v[86:89]
	v_mfma_f32_16x16x32_bf16 v[82:85], v[160:163], v[184:187], v[82:85]
	v_mfma_f32_16x16x32_bf16 v[70:73], v[152:155], v[192:195], v[70:73]
	v_mfma_f32_16x16x32_bf16 v[66:69], v[160:163], v[192:195], v[66:69]
	s_barrier
	s_setprio 0
	s_add_i32 s29, s29, s42
	s_mov_b32 m0, s29
	ds_read_b128 v[164:167], v244 offset:16384
	ds_read_b128 v[168:171], v244 offset:17408
	ds_read_b128 v[172:175], v244 offset:18432
	ds_read_b128 v[176:179], v244 offset:19456
	ds_read_b128 v[180:183], v244 offset:20480
	ds_read_b128 v[184:187], v244 offset:21504
	ds_read_b128 v[188:191], v244 offset:22528
	ds_read_b128 v[192:195], v244 offset:23552
	global_load_lds_dwordx4 v0, s[20:21]
	s_add_i32 m0, s29, 0x2000
	s_add_u32 s52, s20, 0x20000
	s_addc_u32 s53, s21, 0
	s_add_i32 s29, s30, s42
	global_load_lds_dwordx4 v208, s[20:21]
	s_mov_b32 m0, s29
	s_nop 0
	global_load_lds_dwordx4 v0, s[52:53]
	s_add_i32 m0, s29, 0x2000
	s_nop 0
	global_load_lds_dwordx4 v208, s[52:53]
	s_mov_b32 m0, s93
	s_nop 0
	global_load_lds_dwordx4 v204, s[72:73]
	s_mov_b32 m0, s44
	s_nop 0
	global_load_lds_dwordx4 v206, s[72:73]
	s_waitcnt vmcnt(8)
	s_waitcnt lgkmcnt(0)
	s_barrier
	s_setprio 1
	v_mfma_f32_16x16x32_bf16 v[62:65], v[132:135], v[164:167], v[62:65]
	v_mfma_f32_16x16x32_bf16 v[58:61], v[140:143], v[164:167], v[58:61]
	v_mfma_f32_16x16x32_bf16 v[46:49], v[132:135], v[172:175], v[46:49]
	v_mfma_f32_16x16x32_bf16 v[42:45], v[140:143], v[172:175], v[42:45]
	v_mfma_f32_16x16x32_bf16 v[30:33], v[132:135], v[180:183], v[30:33]
	v_mfma_f32_16x16x32_bf16 v[26:29], v[140:143], v[180:183], v[26:29]
	v_mfma_f32_16x16x32_bf16 v[14:17], v[132:135], v[188:191], v[14:17]
	v_mfma_f32_16x16x32_bf16 v[10:13], v[140:143], v[188:191], v[10:13]
	v_mfma_f32_16x16x32_bf16 v[62:65], v[136:139], v[168:171], v[62:65]
	v_mfma_f32_16x16x32_bf16 v[58:61], v[144:147], v[168:171], v[58:61]
	v_mfma_f32_16x16x32_bf16 v[46:49], v[136:139], v[176:179], v[46:49]
	v_mfma_f32_16x16x32_bf16 v[42:45], v[144:147], v[176:179], v[42:45]
	v_mfma_f32_16x16x32_bf16 v[30:33], v[136:139], v[184:187], v[30:33]
	v_mfma_f32_16x16x32_bf16 v[26:29], v[144:147], v[184:187], v[26:29]
	v_mfma_f32_16x16x32_bf16 v[14:17], v[136:139], v[192:195], v[14:17]
	v_mfma_f32_16x16x32_bf16 v[10:13], v[144:147], v[192:195], v[10:13]
	s_setprio 0
	s_setprio 1
	v_mfma_f32_16x16x32_bf16 v[54:57], v[148:151], v[164:167], v[54:57]
	v_mfma_f32_16x16x32_bf16 v[50:53], v[156:159], v[164:167], v[50:53]
	v_mfma_f32_16x16x32_bf16 v[38:41], v[148:151], v[172:175], v[38:41]
	v_mfma_f32_16x16x32_bf16 v[34:37], v[156:159], v[172:175], v[34:37]
	v_mfma_f32_16x16x32_bf16 v[22:25], v[148:151], v[180:183], v[22:25]
	v_mfma_f32_16x16x32_bf16 v[18:21], v[156:159], v[180:183], v[18:21]
	v_mfma_f32_16x16x32_bf16 v[6:9], v[148:151], v[188:191], v[6:9]
	v_mfma_f32_16x16x32_bf16 v[2:5], v[156:159], v[188:191], v[2:5]
	v_mfma_f32_16x16x32_bf16 v[54:57], v[152:155], v[168:171], v[54:57]
	v_mfma_f32_16x16x32_bf16 v[50:53], v[160:163], v[168:171], v[50:53]
	v_mfma_f32_16x16x32_bf16 v[38:41], v[152:155], v[176:179], v[38:41]
	v_mfma_f32_16x16x32_bf16 v[34:37], v[160:163], v[176:179], v[34:37]
	v_mfma_f32_16x16x32_bf16 v[22:25], v[152:155], v[184:187], v[22:25]
	v_mfma_f32_16x16x32_bf16 v[18:21], v[160:163], v[184:187], v[18:21]
	v_mfma_f32_16x16x32_bf16 v[6:9], v[152:155], v[192:195], v[6:9]
	v_mfma_f32_16x16x32_bf16 v[2:5], v[160:163], v[192:195], v[2:5]
	s_barrier
; #define PG8_STAGE(bufoff, gbase, voff) do { _Pragma("unroll") for (int _i = 0; _i < 2; ++_i) \
;         __builtin_amdgcn_global_load_lds((const gunsigned*)((const gchar*)(gbase) + (voff)[_i]), (LAS unsigned*)(lds + (bufoff) + ldsw + _i * 8192), 16, 0, 0); } while (0)
; #define PG8_LDA(dst, b, h) do { _Pragma("unroll") for (int m = 0; m < 4; ++m) _Pragma("unroll") for (int k = 0; k < 2; ++k) dst[m][k] = *(const LAS bf16x8*)(lds + PG8_SA(b, h) + aoff + m * 2048 + k * 1024); } while (0)
; #define PG8_LDB(dst, b, h) do { _Pragma("unroll") for (int n = 0; n < 2; ++n) _Pragma("unroll") for (int k = 0; k < 2; ++k) dst[n][k] = *(const LAS bf16x8*)(lds + PG8_SB(b, h) + boff + n * 2048 + k * 1024); } while (0)
; #define PG8_MMA(ai, bj, At, Bt) do { __builtin_amdgcn_s_setprio(1); _Pragma("unroll") for (int m = 0; m < 4; ++m) _Pragma("unroll") for (int n = 0; n < 2; ++n) _Pragma("unroll") for (int k = 0; k < 2; ++k) \
;         acc[ai][bj][m][n] = __builtin_amdgcn_mfma_f32_16x16x32_bf16(Bt[n][k], At[m][k], acc[ai][bj][m][n], 0, 0, 0); __builtin_amdgcn_s_setprio(0); } while (0)
; #define PG8_WAIT_V(n) asm volatile("s_waitcnt vmcnt(" #n ")" ::: "memory")
; #define PG8_WAIT_L(n) asm volatile("s_waitcnt lgkmcnt(" #n ")" ::: "memory")
; #define PG8_BAR __builtin_amdgcn_s_barrier()
; #define PG8_SCHED __builtin_amdgcn_sched_barrier(0)
; template <class Epi, class Sched>
; __device__ __forceinline__ void gemm_phase(LAS unsigned char* lds, const int tid, const Gemm g, const Sched& S, const Epi& E) {
;     ...
;             PG8_LDB(B0, 1, 0); PG8_LDB(B1, 1, 1); PG8_SCHED; PG8_LDA(At, 1, 0); PG8_STAGE(PG8_SA(0, 1), a2 + hstep, voffA);
;             PG8_WAIT_V(8); PG8_WAIT_L(0); PG8_BAR; PG8_MMA(0, 0, At, B0); PG8_MMA(0, 1, At, B1); PG8_BAR; PG8_SCHED;
;             PG8_LDA(At, 1, 1); PG8_STAGE(PG8_SB(1, 0), b3, voffB); PG8_STAGE(PG8_SB(1, 1), b3 + hstep, voffB); PG8_STAGE(PG8_SA(1, 0), a3, voffA);
;             PG8_WAIT_V(8); PG8_WAIT_L(0); PG8_BAR; PG8_MMA(1, 0, At, B0); PG8_MMA(1, 1, At, B1); PG8_BAR; PG8_SCHED;
;         }
;         if (wr == 0) PG8_BAR;
	s_setprio 0
	s_add_i32 s29, 0, 0x18000
	v_add_u32_e32 v126, s29, v242
	s_add_i32 s30, 0, 0x1c000
	ds_read_b128 v[132:135], v126
	ds_read_b128 v[136:139], v126 offset:1024
	ds_read_b128 v[140:143], v126 offset:2048
	ds_read_b128 v[144:147], v126 offset:3072
	v_add_u32_e32 v126, s30, v242
	ds_read_b128 v[148:151], v126
	ds_read_b128 v[152:155], v126 offset:1024
	ds_read_b128 v[156:159], v126 offset:2048
	ds_read_b128 v[160:163], v126 offset:3072
	s_add_u32 s52, s72, 0x20000
	s_addc_u32 s53, s73, 0
	s_mov_b32 m0, s45
	ds_read_b128 v[164:167], v244 offset:32768
	ds_read_b128 v[168:171], v244 offset:33792
	ds_read_b128 v[172:175], v244 offset:34816
	ds_read_b128 v[176:179], v244 offset:35840
	ds_read_b128 v[180:183], v244 offset:36864
	ds_read_b128 v[184:187], v244 offset:37888
	ds_read_b128 v[188:191], v244 offset:38912
	ds_read_b128 v[192:195], v244 offset:39936
	global_load_lds_dwordx4 v204, s[52:53]
	s_mov_b32 m0, s46
	s_nop 0
	global_load_lds_dwordx4 v206, s[52:53]
	s_waitcnt vmcnt(8)
	s_waitcnt lgkmcnt(0)
	s_barrier
	s_setprio 1
	v_mfma_f32_16x16x32_bf16 v[126:129], v[132:135], v[164:167], v[128:131]
	v_mfma_f32_16x16x32_bf16 v[122:125], v[140:143], v[164:167], v[122:125]
	v_mfma_f32_16x16x32_bf16 v[110:113], v[132:135], v[172:175], v[110:113]
	v_mfma_f32_16x16x32_bf16 v[106:109], v[140:143], v[172:175], v[106:109]
	v_mfma_f32_16x16x32_bf16 v[94:97], v[132:135], v[180:183], v[94:97]
	v_mfma_f32_16x16x32_bf16 v[90:93], v[140:143], v[180:183], v[90:93]
	v_mfma_f32_16x16x32_bf16 v[78:81], v[132:135], v[188:191], v[78:81]
	v_mfma_f32_16x16x32_bf16 v[74:77], v[140:143], v[188:191], v[74:77]
	v_mfma_f32_16x16x32_bf16 v[128:131], v[136:139], v[168:171], v[126:129]
	v_mfma_f32_16x16x32_bf16 v[124:127], v[144:147], v[168:171], v[122:125]
	v_mfma_f32_16x16x32_bf16 v[110:113], v[136:139], v[176:179], v[110:113]
	v_mfma_f32_16x16x32_bf16 v[106:109], v[144:147], v[176:179], v[106:109]
	v_mfma_f32_16x16x32_bf16 v[94:97], v[136:139], v[184:187], v[94:97]
	v_mfma_f32_16x16x32_bf16 v[90:93], v[144:147], v[184:187], v[90:93]
	v_mfma_f32_16x16x32_bf16 v[78:81], v[136:139], v[192:195], v[78:81]
	v_mfma_f32_16x16x32_bf16 v[74:77], v[144:147], v[192:195], v[74:77]
	s_setprio 0
	s_setprio 1
	v_mfma_f32_16x16x32_bf16 v[118:121], v[148:151], v[164:167], v[118:121]
	v_mfma_f32_16x16x32_bf16 v[114:117], v[156:159], v[164:167], v[114:117]
	v_mfma_f32_16x16x32_bf16 v[102:105], v[148:151], v[172:175], v[102:105]
	v_mfma_f32_16x16x32_bf16 v[98:101], v[156:159], v[172:175], v[98:101]
	v_mfma_f32_16x16x32_bf16 v[86:89], v[148:151], v[180:183], v[86:89]
	v_mfma_f32_16x16x32_bf16 v[82:85], v[156:159], v[180:183], v[82:85]
	v_mfma_f32_16x16x32_bf16 v[70:73], v[148:151], v[188:191], v[70:73]
	v_mfma_f32_16x16x32_bf16 v[66:69], v[156:159], v[188:191], v[66:69]
	v_mfma_f32_16x16x32_bf16 v[118:121], v[152:155], v[168:171], v[118:121]
	v_mfma_f32_16x16x32_bf16 v[114:117], v[160:163], v[168:171], v[114:117]
	v_mfma_f32_16x16x32_bf16 v[102:105], v[152:155], v[176:179], v[102:105]
	v_mfma_f32_16x16x32_bf16 v[98:101], v[160:163], v[176:179], v[98:101]
	v_mfma_f32_16x16x32_bf16 v[86:89], v[152:155], v[184:187], v[86:89]
	v_mfma_f32_16x16x32_bf16 v[82:85], v[160:163], v[184:187], v[82:85]
	v_mfma_f32_16x16x32_bf16 v[70:73], v[152:155], v[192:195], v[70:73]
	v_mfma_f32_16x16x32_bf16 v[66:69], v[160:163], v[192:195], v[66:69]
	s_barrier
	s_setprio 0
	s_add_i32 s29, s29, s42
	s_mov_b32 m0, s29
	ds_read_b128 v[164:167], v244 offset:49152
	ds_read_b128 v[168:171], v244 offset:50176
	ds_read_b128 v[172:175], v244 offset:51200
	ds_read_b128 v[176:179], v244 offset:52224
	ds_read_b128 v[180:183], v244 offset:53248
	ds_read_b128 v[184:187], v244 offset:54272
	ds_read_b128 v[188:191], v244 offset:55296
	ds_read_b128 v[192:195], v244 offset:56320
	global_load_lds_dwordx4 v201, s[20:21]
	s_add_i32 m0, s29, 0x2000
	s_add_i32 s29, s30, s42
	global_load_lds_dwordx4 v215, s[20:21]
	s_add_u32 s20, s20, 0x20080
	s_addc_u32 s21, s21, 0
	s_mov_b32 m0, s29
	s_nop 0
	global_load_lds_dwordx4 v0, s[20:21]
	s_add_i32 m0, s29, 0x2000
	s_nop 0
	global_load_lds_dwordx4 v208, s[20:21]
	s_mov_b32 m0, s47
	s_nop 0
	global_load_lds_dwordx4 v217, s[72:73]
	s_mov_b32 m0, s48
	s_nop 0
	global_load_lds_dwordx4 v219, s[72:73]
	s_waitcnt vmcnt(8)
	s_waitcnt lgkmcnt(0)
	s_barrier
	s_setprio 1
	v_mfma_f32_16x16x32_bf16 v[62:65], v[132:135], v[164:167], v[62:65]
	v_mfma_f32_16x16x32_bf16 v[58:61], v[140:143], v[164:167], v[58:61]
	v_mfma_f32_16x16x32_bf16 v[46:49], v[132:135], v[172:175], v[46:49]
	v_mfma_f32_16x16x32_bf16 v[42:45], v[140:143], v[172:175], v[42:45]
	v_mfma_f32_16x16x32_bf16 v[30:33], v[132:135], v[180:183], v[30:33]
	v_mfma_f32_16x16x32_bf16 v[26:29], v[140:143], v[180:183], v[26:29]
	v_mfma_f32_16x16x32_bf16 v[14:17], v[132:135], v[188:191], v[14:17]
	v_mfma_f32_16x16x32_bf16 v[10:13], v[140:143], v[188:191], v[10:13]
	v_mfma_f32_16x16x32_bf16 v[62:65], v[136:139], v[168:171], v[62:65]
	v_mfma_f32_16x16x32_bf16 v[58:61], v[144:147], v[168:171], v[58:61]
	v_mfma_f32_16x16x32_bf16 v[46:49], v[136:139], v[176:179], v[46:49]
	v_mfma_f32_16x16x32_bf16 v[42:45], v[144:147], v[176:179], v[42:45]
	v_mfma_f32_16x16x32_bf16 v[30:33], v[136:139], v[184:187], v[30:33]
	v_mfma_f32_16x16x32_bf16 v[26:29], v[144:147], v[184:187], v[26:29]
	v_mfma_f32_16x16x32_bf16 v[14:17], v[136:139], v[192:195], v[14:17]
	v_mfma_f32_16x16x32_bf16 v[10:13], v[144:147], v[192:195], v[10:13]
	s_setprio 0
	s_setprio 1
	v_mfma_f32_16x16x32_bf16 v[54:57], v[148:151], v[164:167], v[54:57]
	v_mfma_f32_16x16x32_bf16 v[50:53], v[156:159], v[164:167], v[50:53]
	v_mfma_f32_16x16x32_bf16 v[38:41], v[148:151], v[172:175], v[38:41]
	v_mfma_f32_16x16x32_bf16 v[34:37], v[156:159], v[172:175], v[34:37]
	v_mfma_f32_16x16x32_bf16 v[22:25], v[148:151], v[180:183], v[22:25]
	v_mfma_f32_16x16x32_bf16 v[18:21], v[156:159], v[180:183], v[18:21]
	v_mfma_f32_16x16x32_bf16 v[6:9], v[148:151], v[188:191], v[6:9]
	v_mfma_f32_16x16x32_bf16 v[2:5], v[156:159], v[188:191], v[2:5]
	v_mfma_f32_16x16x32_bf16 v[54:57], v[152:155], v[168:171], v[54:57]
	v_mfma_f32_16x16x32_bf16 v[50:53], v[160:163], v[168:171], v[50:53]
	v_mfma_f32_16x16x32_bf16 v[38:41], v[152:155], v[176:179], v[38:41]
	v_mfma_f32_16x16x32_bf16 v[34:37], v[160:163], v[176:179], v[34:37]
	v_mfma_f32_16x16x32_bf16 v[22:25], v[152:155], v[184:187], v[22:25]
	v_mfma_f32_16x16x32_bf16 v[18:21], v[160:163], v[184:187], v[18:21]
	v_mfma_f32_16x16x32_bf16 v[6:9], v[152:155], v[192:195], v[6:9]
	v_mfma_f32_16x16x32_bf16 v[2:5], v[160:163], v[192:195], v[2:5]
	s_barrier
	s_setprio 0
	s_add_i32 s51, s51, 2
	s_add_u32 s24, s24, 0x100
	s_addc_u32 s31, s31, 0
	s_add_u32 s16, s16, 0x100
	s_addc_u32 s17, s17, 0
	s_cmp_gt_u32 s51, 5
	s_cbranch_scc0 .LBB0_444
	s_and_b64 vcc, exec, s[10:11]
	s_cbranch_vccz .LBB0_447
	s_barrier

; #define PG8_STAGE(bufoff, gbase, voff) do { _Pragma("unroll") for (int _i = 0; _i < 2; ++_i) \
;         __builtin_amdgcn_global_load_lds((const gunsigned*)((const gchar*)(gbase) + (voff)[_i]), (LAS unsigned*)(lds + (bufoff) + ldsw + _i * 8192), 16, 0, 0); } while (0)
; #define PG8_LDA(dst, b, h) do { _Pragma("unroll") for (int m = 0; m < 4; ++m) _Pragma("unroll") for (int k = 0; k < 2; ++k) dst[m][k] = *(const LAS bf16x8*)(lds + PG8_SA(b, h) + aoff + m * 2048 + k * 1024); } while (0)
; #define PG8_LDB(dst, b, h) do { _Pragma("unroll") for (int n = 0; n < 2; ++n) _Pragma("unroll") for (int k = 0; k < 2; ++k) dst[n][k] = *(const LAS bf16x8*)(lds + PG8_SB(b, h) + boff + n * 2048 + k * 1024); } while (0)
; #define PG8_MMA(ai, bj, At, Bt) do { __builtin_amdgcn_s_setprio(1); _Pragma("unroll") for (int m = 0; m < 4; ++m) _Pragma("unroll") for (int n = 0; n < 2; ++n) _Pragma("unroll") for (int k = 0; k < 2; ++k) \
;         acc[ai][bj][m][n] = __builtin_amdgcn_mfma_f32_16x16x32_bf16(Bt[n][k], At[m][k], acc[ai][bj][m][n], 0, 0, 0); __builtin_amdgcn_s_setprio(0); } while (0)
; #define PG8_WAIT_V(n) asm volatile("s_waitcnt vmcnt(" #n ")" ::: "memory")
; #define PG8_WAIT_L(n) asm volatile("s_waitcnt lgkmcnt(" #n ")" ::: "memory")
; #define PG8_BAR __builtin_amdgcn_s_barrier()
; #define PG8_SCHED __builtin_amdgcn_sched_barrier(0)
; template <class Epi, class Sched>
; __device__ __forceinline__ void gemm_phase(LAS unsigned char* lds, const int tid, const Gemm g, const Sched& S, const Epi& E) {
;     ...
;             const bool last = (t == nt - 2);
;             const gchar* a1 = cA + (size_t)(t + 1) * kstep;
;             const gchar* a2 = last ? nA : cA + (size_t)(t + 2) * kstep; const gchar* b2 = last ? nB : cB + (size_t)(t + 2) * kstep;
;             const gchar* a3 = a2 + kstep; const gchar* b3 = b2 + kstep;
;             PG8_LDB(B0, 0, 0); PG8_LDB(B1, 0, 1); PG8_SCHED; PG8_LDA(At, 0, 0); PG8_STAGE(PG8_SA(1, 1), a1 + hstep, voffA);
;             PG8_WAIT_V(8); PG8_WAIT_L(0); PG8_BAR; PG8_MMA(0, 0, At, B0); PG8_MMA(0, 1, At, B1); PG8_BAR; PG8_SCHED;
;             PG8_LDA(At, 0, 1); PG8_STAGE(PG8_SB(0, 0), b2, voffB); PG8_STAGE(PG8_SB(0, 1), b2 + hstep, voffB); PG8_STAGE(PG8_SA(0, 0), a2, voffA);
;             PG8_WAIT_V(8); PG8_WAIT_L(0); PG8_BAR; PG8_MMA(1, 0, At, B0); PG8_MMA(1, 1, At, B1); PG8_BAR; PG8_SCHED;
.LBB0_559:
	s_add_u32 s20, s60, 0xfffc0080
	s_addc_u32 s21, s61, -1
	s_add_i32 s29, 0, 0x10000
	s_cmp_eq_u32 s46, 12
	s_cselect_b32 s63, s9, s21
	s_cselect_b32 s62, s42, s20
	s_cselect_b32 s21, s7, s45
	s_cselect_b32 s20, s43, s44
	s_add_i32 s30, 0, 0x14000
	v_add_u32_e32 v152, s29, v165
	v_add_u32_e32 v160, s30, v165
	ds_read_b128 v[130:133], v152
	ds_read_b128 v[144:147], v152 offset:1024
	ds_read_b128 v[148:151], v152 offset:2048
	ds_read_b128 v[152:155], v152 offset:3072
	ds_read_b128 v[156:159], v160
	ds_read_b128 v[170:173], v160 offset:1024
	ds_read_b128 v[174:177], v160 offset:2048
	ds_read_b128 v[178:181], v160 offset:3072
	s_add_i32 m0, s34, 0xc000
	ds_read_b128 v[182:185], v169
	ds_read_b128 v[186:189], v169 offset:1024
	ds_read_b128 v[190:193], v169 offset:2048
	ds_read_b128 v[204:207], v169 offset:3072
	ds_read_b128 v[210:213], v169 offset:4096
	ds_read_b128 v[214:217], v169 offset:5120
	ds_read_b128 v[218:221], v169 offset:6144
	ds_read_b128 v[222:225], v169 offset:7168
	global_load_lds_dwordx4 v142, s[60:61]
	s_add_i32 m0, s34, 0xe000
	s_nop 0
	global_load_lds_dwordx4 v140, s[60:61]
	s_waitcnt vmcnt(8)
	s_waitcnt lgkmcnt(0)
	s_barrier
	s_setprio 1
	v_mfma_f32_16x16x32_bf16 v[126:129], v[130:133], v[182:185], v[126:129]
	v_mfma_f32_16x16x32_bf16 v[122:125], v[148:151], v[182:185], v[122:125]
	v_mfma_f32_16x16x32_bf16 v[118:121], v[130:133], v[190:193], v[118:121]
	v_mfma_f32_16x16x32_bf16 v[110:113], v[148:151], v[190:193], v[110:113]
	v_mfma_f32_16x16x32_bf16 v[102:105], v[130:133], v[210:213], v[102:105]
	v_mfma_f32_16x16x32_bf16 v[94:97], v[148:151], v[210:213], v[94:97]
	v_mfma_f32_16x16x32_bf16 v[86:89], v[130:133], v[218:221], v[86:89]
	v_mfma_f32_16x16x32_bf16 v[78:81], v[148:151], v[218:221], v[78:81]
	v_mfma_f32_16x16x32_bf16 v[126:129], v[144:147], v[186:189], v[126:129]
	v_mfma_f32_16x16x32_bf16 v[122:125], v[152:155], v[186:189], v[122:125]
	v_mfma_f32_16x16x32_bf16 v[118:121], v[144:147], v[204:207], v[118:121]
	v_mfma_f32_16x16x32_bf16 v[110:113], v[152:155], v[204:207], v[110:113]
	v_mfma_f32_16x16x32_bf16 v[102:105], v[144:147], v[214:217], v[102:105]
	v_mfma_f32_16x16x32_bf16 v[94:97], v[152:155], v[214:217], v[94:97]
	v_mfma_f32_16x16x32_bf16 v[86:89], v[144:147], v[222:225], v[86:89]
	v_mfma_f32_16x16x32_bf16 v[78:81], v[152:155], v[222:225], v[78:81]
	s_setprio 0
	s_setprio 1
	v_mfma_f32_16x16x32_bf16 v[114:117], v[156:159], v[182:185], v[114:117]
	v_mfma_f32_16x16x32_bf16 v[106:109], v[174:177], v[182:185], v[106:109]
	v_mfma_f32_16x16x32_bf16 v[98:101], v[156:159], v[190:193], v[98:101]
	v_mfma_f32_16x16x32_bf16 v[90:93], v[174:177], v[190:193], v[90:93]
	v_mfma_f32_16x16x32_bf16 v[82:85], v[156:159], v[210:213], v[82:85]
	v_mfma_f32_16x16x32_bf16 v[74:77], v[174:177], v[210:213], v[74:77]
	v_mfma_f32_16x16x32_bf16 v[70:73], v[156:159], v[218:221], v[70:73]
	v_mfma_f32_16x16x32_bf16 v[66:69], v[174:177], v[218:221], v[66:69]
	v_mfma_f32_16x16x32_bf16 v[114:117], v[170:173], v[186:189], v[114:117]
	v_mfma_f32_16x16x32_bf16 v[106:109], v[178:181], v[186:189], v[106:109]
	v_mfma_f32_16x16x32_bf16 v[98:101], v[170:173], v[204:207], v[98:101]
	v_mfma_f32_16x16x32_bf16 v[90:93], v[178:181], v[204:207], v[90:93]
	v_mfma_f32_16x16x32_bf16 v[82:85], v[170:173], v[214:217], v[82:85]
	v_mfma_f32_16x16x32_bf16 v[74:77], v[178:181], v[214:217], v[74:77]
	v_mfma_f32_16x16x32_bf16 v[70:73], v[170:173], v[222:225], v[70:73]
	v_mfma_f32_16x16x32_bf16 v[66:69], v[178:181], v[222:225], v[66:69]
	s_barrier
	s_setprio 0
	s_add_i32 s29, s29, s12
	s_mov_b32 m0, s29
	ds_read_b128 v[182:185], v169 offset:16384
	ds_read_b128 v[186:189], v169 offset:17408
	ds_read_b128 v[190:193], v169 offset:18432
	ds_read_b128 v[204:207], v169 offset:19456
	ds_read_b128 v[210:213], v169 offset:20480
	ds_read_b128 v[214:217], v169 offset:21504
	ds_read_b128 v[218:221], v169 offset:22528
	ds_read_b128 v[222:225], v169 offset:23552
	global_load_lds_dwordx4 v0, s[20:21]
	s_add_i32 m0, s29, 0x2000
	s_add_u32 s48, s20, 0x40000
	s_addc_u32 s49, s21, 0
	s_add_i32 s29, s30, s12
	global_load_lds_dwordx4 v134, s[20:21]
	s_mov_b32 m0, s29
	s_nop 0
	global_load_lds_dwordx4 v0, s[48:49]
	s_add_i32 m0, s29, 0x2000
	s_nop 0
	global_load_lds_dwordx4 v134, s[48:49]
	s_mov_b32 m0, s34
	s_nop 0
	global_load_lds_dwordx4 v138, s[62:63]
	s_mov_b32 m0, s35
	s_nop 0
	global_load_lds_dwordx4 v136, s[62:63]
	s_waitcnt vmcnt(8)
	s_waitcnt lgkmcnt(0)
	s_barrier
	s_setprio 1
	v_mfma_f32_16x16x32_bf16 v[62:65], v[130:133], v[182:185], v[62:65]
	v_mfma_f32_16x16x32_bf16 v[58:61], v[148:151], v[182:185], v[58:61]
	v_mfma_f32_16x16x32_bf16 v[54:57], v[130:133], v[190:193], v[54:57]
	v_mfma_f32_16x16x32_bf16 v[46:49], v[148:151], v[190:193], v[46:49]
	v_mfma_f32_16x16x32_bf16 v[38:41], v[130:133], v[210:213], v[38:41]
	v_mfma_f32_16x16x32_bf16 v[30:33], v[148:151], v[210:213], v[30:33]
	v_mfma_f32_16x16x32_bf16 v[22:25], v[130:133], v[218:221], v[22:25]
	v_mfma_f32_16x16x32_bf16 v[14:17], v[148:151], v[218:221], v[14:17]
	v_mfma_f32_16x16x32_bf16 v[62:65], v[144:147], v[186:189], v[62:65]
	v_mfma_f32_16x16x32_bf16 v[58:61], v[152:155], v[186:189], v[58:61]
	v_mfma_f32_16x16x32_bf16 v[54:57], v[144:147], v[204:207], v[54:57]
	v_mfma_f32_16x16x32_bf16 v[46:49], v[152:155], v[204:207], v[46:49]
	v_mfma_f32_16x16x32_bf16 v[38:41], v[144:147], v[214:217], v[38:41]
	v_mfma_f32_16x16x32_bf16 v[30:33], v[152:155], v[214:217], v[30:33]
	v_mfma_f32_16x16x32_bf16 v[22:25], v[144:147], v[222:225], v[22:25]
	v_mfma_f32_16x16x32_bf16 v[14:17], v[152:155], v[222:225], v[14:17]
	s_setprio 0
	s_setprio 1
	v_mfma_f32_16x16x32_bf16 v[50:53], v[156:159], v[182:185], v[50:53]
	v_mfma_f32_16x16x32_bf16 v[42:45], v[174:177], v[182:185], v[42:45]
	v_mfma_f32_16x16x32_bf16 v[34:37], v[156:159], v[190:193], v[34:37]
	v_mfma_f32_16x16x32_bf16 v[26:29], v[174:177], v[190:193], v[26:29]
	v_mfma_f32_16x16x32_bf16 v[18:21], v[156:159], v[210:213], v[18:21]
	v_mfma_f32_16x16x32_bf16 v[10:13], v[174:177], v[210:213], v[10:13]
	v_mfma_f32_16x16x32_bf16 v[6:9], v[156:159], v[218:221], v[6:9]
	v_mfma_f32_16x16x32_bf16 v[2:5], v[174:177], v[218:221], v[2:5]
	v_mfma_f32_16x16x32_bf16 v[50:53], v[170:173], v[186:189], v[50:53]
	v_mfma_f32_16x16x32_bf16 v[42:45], v[178:181], v[186:189], v[42:45]
	v_mfma_f32_16x16x32_bf16 v[34:37], v[170:173], v[204:207], v[34:37]
	v_mfma_f32_16x16x32_bf16 v[26:29], v[178:181], v[204:207], v[26:29]
	v_mfma_f32_16x16x32_bf16 v[18:21], v[170:173], v[214:217], v[18:21]
	v_mfma_f32_16x16x32_bf16 v[10:13], v[178:181], v[214:217], v[10:13]
	v_mfma_f32_16x16x32_bf16 v[6:9], v[170:173], v[222:225], v[6:9]
	v_mfma_f32_16x16x32_bf16 v[2:5], v[178:181], v[222:225], v[2:5]
	s_barrier
; #define PG8_STAGE(bufoff, gbase, voff) do { _Pragma("unroll") for (int _i = 0; _i < 2; ++_i) \
;         __builtin_amdgcn_global_load_lds((const gunsigned*)((const gchar*)(gbase) + (voff)[_i]), (LAS unsigned*)(lds + (bufoff) + ldsw + _i * 8192), 16, 0, 0); } while (0)
; #define PG8_LDA(dst, b, h) do { _Pragma("unroll") for (int m = 0; m < 4; ++m) _Pragma("unroll") for (int k = 0; k < 2; ++k) dst[m][k] = *(const LAS bf16x8*)(lds + PG8_SA(b, h) + aoff + m * 2048 + k * 1024); } while (0)
; #define PG8_LDB(dst, b, h) do { _Pragma("unroll") for (int n = 0; n < 2; ++n) _Pragma("unroll") for (int k = 0; k < 2; ++k) dst[n][k] = *(const LAS bf16x8*)(lds + PG8_SB(b, h) + boff + n * 2048 + k * 1024); } while (0)
; #define PG8_MMA(ai, bj, At, Bt) do { __builtin_amdgcn_s_setprio(1); _Pragma("unroll") for (int m = 0; m < 4; ++m) _Pragma("unroll") for (int n = 0; n < 2; ++n) _Pragma("unroll") for (int k = 0; k < 2; ++k) \
;         acc[ai][bj][m][n] = __builtin_amdgcn_mfma_f32_16x16x32_bf16(Bt[n][k], At[m][k], acc[ai][bj][m][n], 0, 0, 0); __builtin_amdgcn_s_setprio(0); } while (0)
; #define PG8_WAIT_V(n) asm volatile("s_waitcnt vmcnt(" #n ")" ::: "memory")
; #define PG8_WAIT_L(n) asm volatile("s_waitcnt lgkmcnt(" #n ")" ::: "memory")
; #define PG8_BAR __builtin_amdgcn_s_barrier()
; #define PG8_SCHED __builtin_amdgcn_sched_barrier(0)
; template <class Epi, class Sched>
; __device__ __forceinline__ void gemm_phase(LAS unsigned char* lds, const int tid, const Gemm g, const Sched& S, const Epi& E) {
;     ...
;             PG8_LDB(B0, 1, 0); PG8_LDB(B1, 1, 1); PG8_SCHED; PG8_LDA(At, 1, 0); PG8_STAGE(PG8_SA(0, 1), a2 + hstep, voffA);
;             PG8_WAIT_V(8); PG8_WAIT_L(0); PG8_BAR; PG8_MMA(0, 0, At, B0); PG8_MMA(0, 1, At, B1); PG8_BAR; PG8_SCHED;
;             PG8_LDA(At, 1, 1); PG8_STAGE(PG8_SB(1, 0), b3, voffB); PG8_STAGE(PG8_SB(1, 1), b3 + hstep, voffB); PG8_STAGE(PG8_SA(1, 0), a3, voffA);
;             PG8_WAIT_V(8); PG8_WAIT_L(0); PG8_BAR; PG8_MMA(1, 0, At, B0); PG8_MMA(1, 1, At, B1); PG8_BAR; PG8_SCHED;
;         }
;         if (wr == 0) PG8_BAR;
	s_setprio 0
	s_add_i32 s29, 0, 0x18000
	s_add_i32 s30, 0, 0x1c000
	v_add_u32_e32 v152, s29, v165
	v_add_u32_e32 v162, s30, v165
	ds_read_b128 v[130:133], v152
	ds_read_b128 v[144:147], v152 offset:1024
	ds_read_b128 v[148:151], v152 offset:2048
	ds_read_b128 v[152:155], v152 offset:3072
	ds_read_b128 v[156:159], v162
	ds_read_b128 v[170:173], v162 offset:1024
	ds_read_b128 v[174:177], v162 offset:2048
	ds_read_b128 v[178:181], v162 offset:3072
	s_add_u32 s48, s62, 0x40000
	s_addc_u32 s49, s63, 0
	s_mov_b32 m0, s36
	ds_read_b128 v[182:185], v169 offset:32768
	ds_read_b128 v[186:189], v169 offset:33792
	ds_read_b128 v[190:193], v169 offset:34816
	ds_read_b128 v[204:207], v169 offset:35840
	ds_read_b128 v[210:213], v169 offset:36864
	ds_read_b128 v[214:217], v169 offset:37888
	ds_read_b128 v[218:221], v169 offset:38912
	ds_read_b128 v[222:225], v169 offset:39936
	global_load_lds_dwordx4 v138, s[48:49]
	s_mov_b32 m0, s37
	s_nop 0
	global_load_lds_dwordx4 v136, s[48:49]
	s_waitcnt vmcnt(8)
	s_waitcnt lgkmcnt(0)
	s_barrier
	s_setprio 1
	v_mfma_f32_16x16x32_bf16 v[126:129], v[130:133], v[182:185], v[126:129]
	v_mfma_f32_16x16x32_bf16 v[122:125], v[148:151], v[182:185], v[122:125]
	v_mfma_f32_16x16x32_bf16 v[118:121], v[130:133], v[190:193], v[118:121]
	v_mfma_f32_16x16x32_bf16 v[110:113], v[148:151], v[190:193], v[110:113]
	v_mfma_f32_16x16x32_bf16 v[102:105], v[130:133], v[210:213], v[102:105]
	v_mfma_f32_16x16x32_bf16 v[94:97], v[148:151], v[210:213], v[94:97]
	v_mfma_f32_16x16x32_bf16 v[86:89], v[130:133], v[218:221], v[86:89]
	v_mfma_f32_16x16x32_bf16 v[78:81], v[148:151], v[218:221], v[78:81]
	v_mfma_f32_16x16x32_bf16 v[126:129], v[144:147], v[186:189], v[126:129]
	v_mfma_f32_16x16x32_bf16 v[122:125], v[152:155], v[186:189], v[122:125]
	v_mfma_f32_16x16x32_bf16 v[118:121], v[144:147], v[204:207], v[118:121]
	v_mfma_f32_16x16x32_bf16 v[110:113], v[152:155], v[204:207], v[110:113]
	v_mfma_f32_16x16x32_bf16 v[102:105], v[144:147], v[214:217], v[102:105]
	v_mfma_f32_16x16x32_bf16 v[94:97], v[152:155], v[214:217], v[94:97]
	v_mfma_f32_16x16x32_bf16 v[86:89], v[144:147], v[222:225], v[86:89]
	v_mfma_f32_16x16x32_bf16 v[78:81], v[152:155], v[222:225], v[78:81]
	s_setprio 0
	s_setprio 1
	v_mfma_f32_16x16x32_bf16 v[114:117], v[156:159], v[182:185], v[114:117]
	v_mfma_f32_16x16x32_bf16 v[106:109], v[174:177], v[182:185], v[106:109]
	v_mfma_f32_16x16x32_bf16 v[98:101], v[156:159], v[190:193], v[98:101]
	v_mfma_f32_16x16x32_bf16 v[90:93], v[174:177], v[190:193], v[90:93]
	v_mfma_f32_16x16x32_bf16 v[82:85], v[156:159], v[210:213], v[82:85]
	v_mfma_f32_16x16x32_bf16 v[74:77], v[174:177], v[210:213], v[74:77]
	v_mfma_f32_16x16x32_bf16 v[70:73], v[156:159], v[218:221], v[70:73]
	v_mfma_f32_16x16x32_bf16 v[66:69], v[174:177], v[218:221], v[66:69]
	v_mfma_f32_16x16x32_bf16 v[114:117], v[170:173], v[186:189], v[114:117]
	v_mfma_f32_16x16x32_bf16 v[106:109], v[178:181], v[186:189], v[106:109]
	v_mfma_f32_16x16x32_bf16 v[98:101], v[170:173], v[204:207], v[98:101]
	v_mfma_f32_16x16x32_bf16 v[90:93], v[178:181], v[204:207], v[90:93]
	v_mfma_f32_16x16x32_bf16 v[82:85], v[170:173], v[214:217], v[82:85]
	v_mfma_f32_16x16x32_bf16 v[74:77], v[178:181], v[214:217], v[74:77]
	v_mfma_f32_16x16x32_bf16 v[70:73], v[170:173], v[222:225], v[70:73]
	v_mfma_f32_16x16x32_bf16 v[66:69], v[178:181], v[222:225], v[66:69]
	s_barrier
	s_setprio 0
	s_add_i32 s29, s29, s12
	s_mov_b32 m0, s29
	ds_read_b128 v[182:185], v169 offset:49152
	ds_read_b128 v[186:189], v169 offset:50176
	ds_read_b128 v[190:193], v169 offset:51200
	ds_read_b128 v[204:207], v169 offset:52224
	ds_read_b128 v[210:213], v169 offset:53248
	ds_read_b128 v[214:217], v169 offset:54272
	ds_read_b128 v[218:221], v169 offset:55296
	ds_read_b128 v[222:225], v169 offset:56320
	global_load_lds_dwordx4 v161, s[20:21]
	s_add_i32 m0, s29, 0x2000
	s_add_i32 s29, s30, s12
	global_load_lds_dwordx4 v195, s[20:21]
	s_add_u32 s20, s20, 0x40080
	s_addc_u32 s21, s21, 0
	s_mov_b32 m0, s29
	s_nop 0
	global_load_lds_dwordx4 v0, s[20:21]
	s_add_i32 m0, s29, 0x2000
	s_nop 0
	global_load_lds_dwordx4 v134, s[20:21]
	s_mov_b32 m0, s38
	s_nop 0
	global_load_lds_dwordx4 v201, s[62:63]
	s_mov_b32 m0, s39
	s_nop 0
	global_load_lds_dwordx4 v227, s[62:63]
	s_waitcnt vmcnt(8)
	s_waitcnt lgkmcnt(0)
	s_barrier
	s_setprio 1
	v_mfma_f32_16x16x32_bf16 v[62:65], v[130:133], v[182:185], v[62:65]
	v_mfma_f32_16x16x32_bf16 v[58:61], v[148:151], v[182:185], v[58:61]
	v_mfma_f32_16x16x32_bf16 v[54:57], v[130:133], v[190:193], v[54:57]
	v_mfma_f32_16x16x32_bf16 v[46:49], v[148:151], v[190:193], v[46:49]
	v_mfma_f32_16x16x32_bf16 v[38:41], v[130:133], v[210:213], v[38:41]
	v_mfma_f32_16x16x32_bf16 v[30:33], v[148:151], v[210:213], v[30:33]
	v_mfma_f32_16x16x32_bf16 v[22:25], v[130:133], v[218:221], v[22:25]
	v_mfma_f32_16x16x32_bf16 v[14:17], v[148:151], v[218:221], v[14:17]
	v_mfma_f32_16x16x32_bf16 v[62:65], v[144:147], v[186:189], v[62:65]
	v_mfma_f32_16x16x32_bf16 v[58:61], v[152:155], v[186:189], v[58:61]
	v_mfma_f32_16x16x32_bf16 v[54:57], v[144:147], v[204:207], v[54:57]
	v_mfma_f32_16x16x32_bf16 v[46:49], v[152:155], v[204:207], v[46:49]
	v_mfma_f32_16x16x32_bf16 v[38:41], v[144:147], v[214:217], v[38:41]
	v_mfma_f32_16x16x32_bf16 v[30:33], v[152:155], v[214:217], v[30:33]
	v_mfma_f32_16x16x32_bf16 v[22:25], v[144:147], v[222:225], v[22:25]
	v_mfma_f32_16x16x32_bf16 v[14:17], v[152:155], v[222:225], v[14:17]
	s_setprio 0
	s_setprio 1
	v_mfma_f32_16x16x32_bf16 v[50:53], v[156:159], v[182:185], v[50:53]
	v_mfma_f32_16x16x32_bf16 v[42:45], v[174:177], v[182:185], v[42:45]
	v_mfma_f32_16x16x32_bf16 v[34:37], v[156:159], v[190:193], v[34:37]
	v_mfma_f32_16x16x32_bf16 v[26:29], v[174:177], v[190:193], v[26:29]
	v_mfma_f32_16x16x32_bf16 v[18:21], v[156:159], v[210:213], v[18:21]
	v_mfma_f32_16x16x32_bf16 v[10:13], v[174:177], v[210:213], v[10:13]
	v_mfma_f32_16x16x32_bf16 v[6:9], v[156:159], v[218:221], v[6:9]
	v_mfma_f32_16x16x32_bf16 v[2:5], v[174:177], v[218:221], v[2:5]
	v_mfma_f32_16x16x32_bf16 v[50:53], v[170:173], v[186:189], v[50:53]
	v_mfma_f32_16x16x32_bf16 v[42:45], v[178:181], v[186:189], v[42:45]
	v_mfma_f32_16x16x32_bf16 v[34:37], v[170:173], v[204:207], v[34:37]
	v_mfma_f32_16x16x32_bf16 v[26:29], v[178:181], v[204:207], v[26:29]
	v_mfma_f32_16x16x32_bf16 v[18:21], v[170:173], v[214:217], v[18:21]
	v_mfma_f32_16x16x32_bf16 v[10:13], v[178:181], v[214:217], v[10:13]
	v_mfma_f32_16x16x32_bf16 v[6:9], v[170:173], v[222:225], v[6:9]
	v_mfma_f32_16x16x32_bf16 v[2:5], v[178:181], v[222:225], v[2:5]
	s_barrier
	s_setprio 0
	s_add_i32 s46, s46, 2
	s_add_u32 s44, s44, 0x100
	s_addc_u32 s45, s45, 0
	s_add_u32 s60, s60, 0x100
	s_addc_u32 s61, s61, 0
	s_cmp_gt_u32 s46, 13
	s_cbranch_scc0 .LBB0_559
	s_and_b64 vcc, exec, s[4:5]
	s_cbranch_vccz .LBB0_562
	s_barrier

; #define PG8_STAGE(bufoff, gbase, voff) do { _Pragma("unroll") for (int _i = 0; _i < 2; ++_i) \
;         __builtin_amdgcn_global_load_lds((const gunsigned*)((const gchar*)(gbase) + (voff)[_i]), (LAS unsigned*)(lds + (bufoff) + ldsw + _i * 8192), 16, 0, 0); } while (0)
; #define PG8_LDA(dst, b, h) do { _Pragma("unroll") for (int m = 0; m < 4; ++m) _Pragma("unroll") for (int k = 0; k < 2; ++k) dst[m][k] = *(const LAS bf16x8*)(lds + PG8_SA(b, h) + aoff + m * 2048 + k * 1024); } while (0)
; #define PG8_LDB(dst, b, h) do { _Pragma("unroll") for (int n = 0; n < 2; ++n) _Pragma("unroll") for (int k = 0; k < 2; ++k) dst[n][k] = *(const LAS bf16x8*)(lds + PG8_SB(b, h) + boff + n * 2048 + k * 1024); } while (0)
; #define PG8_MMA(ai, bj, At, Bt) do { __builtin_amdgcn_s_setprio(1); _Pragma("unroll") for (int m = 0; m < 4; ++m) _Pragma("unroll") for (int n = 0; n < 2; ++n) _Pragma("unroll") for (int k = 0; k < 2; ++k) \
;         acc[ai][bj][m][n] = __builtin_amdgcn_mfma_f32_16x16x32_bf16(Bt[n][k], At[m][k], acc[ai][bj][m][n], 0, 0, 0); __builtin_amdgcn_s_setprio(0); } while (0)
; #define PG8_WAIT_V(n) asm volatile("s_waitcnt vmcnt(" #n ")" ::: "memory")
; #define PG8_WAIT_L(n) asm volatile("s_waitcnt lgkmcnt(" #n ")" ::: "memory")
; #define PG8_BAR __builtin_amdgcn_s_barrier()
; #define PG8_SCHED __builtin_amdgcn_sched_barrier(0)
; template <class Epi, class Sched>
; __device__ __forceinline__ void gemm_phase(LAS unsigned char* lds, const int tid, const Gemm g, const Sched& S, const Epi& E) {
;     ...
;         for (int t = 0; t < nt; t += 2) {
;             const bool last = (t == nt - 2);
;             const gchar* a1 = cA + (size_t)(t + 1) * kstep;
;             const gchar* a2 = last ? nA : cA + (size_t)(t + 2) * kstep; const gchar* b2 = last ? nB : cB + (size_t)(t + 2) * kstep;
;             const gchar* a3 = a2 + kstep; const gchar* b3 = b2 + kstep;
;             PG8_LDB(B0, 0, 0); PG8_LDB(B1, 0, 1); PG8_SCHED; PG8_LDA(At, 0, 0); PG8_STAGE(PG8_SA(1, 1), a1 + hstep, voffA);
;             PG8_WAIT_V(8); PG8_WAIT_L(0); PG8_BAR; PG8_MMA(0, 0, At, B0); PG8_MMA(0, 1, At, B1); PG8_BAR; PG8_SCHED;
;             PG8_LDA(At, 0, 1); PG8_STAGE(PG8_SB(0, 0), b2, voffB); PG8_STAGE(PG8_SB(0, 1), b2 + hstep, voffB); PG8_STAGE(PG8_SA(0, 0), a2, voffA);
;             PG8_WAIT_V(8); PG8_WAIT_L(0); PG8_BAR; PG8_MMA(1, 0, At, B0); PG8_MMA(1, 1, At, B1); PG8_BAR; PG8_SCHED;
.LBB0_598:
	s_add_u32 s20, s62, 0x100
	s_addc_u32 s21, s63, 0
	s_add_i32 s29, 0, 0x10000
	s_cmp_eq_u32 s45, 40
	s_cselect_b32 s73, s9, s21
	s_cselect_b32 s72, s8, s20
	s_cselect_b32 s67, s61, s44
	s_cselect_b32 s66, s60, s31
	s_add_i32 s48, 0, 0x14000
	v_add_u32_e32 v142, s29, v210
	v_add_u32_e32 v158, s48, v210
	ds_read_b128 v[130:133], v142
	ds_read_b128 v[134:137], v142 offset:1024
	ds_read_b128 v[138:141], v142 offset:2048
	ds_read_b128 v[142:145], v142 offset:3072
	ds_read_b128 v[146:149], v158
	ds_read_b128 v[150:153], v158 offset:1024
	ds_read_b128 v[154:157], v158 offset:2048
	ds_read_b128 v[158:161], v158 offset:3072
	s_add_i32 m0, s34, 0xc000
	ds_read_b128 v[162:165], v214
	ds_read_b128 v[166:169], v214 offset:1024
	ds_read_b128 v[170:173], v214 offset:2048
	ds_read_b128 v[174:177], v214 offset:3072
	ds_read_b128 v[188:191], v214 offset:4096
	ds_read_b128 v[192:195], v214 offset:5120
	ds_read_b128 v[204:207], v214 offset:6144
	ds_read_b128 v[216:219], v214 offset:7168
	global_load_lds_dwordx4 v186, s[62:63]
	s_add_i32 m0, s34, 0xe000
	s_nop 0
	global_load_lds_dwordx4 v184, s[62:63]
	s_waitcnt vmcnt(8)
	s_waitcnt lgkmcnt(0)
	s_barrier
	s_setprio 1
	v_mfma_f32_16x16x32_bf16 v[126:129], v[130:133], v[162:165], v[126:129]
	v_mfma_f32_16x16x32_bf16 v[122:125], v[138:141], v[162:165], v[122:125]
	v_mfma_f32_16x16x32_bf16 v[110:113], v[130:133], v[170:173], v[110:113]
	v_mfma_f32_16x16x32_bf16 v[106:109], v[138:141], v[170:173], v[106:109]
	v_mfma_f32_16x16x32_bf16 v[94:97], v[130:133], v[188:191], v[94:97]
	v_mfma_f32_16x16x32_bf16 v[90:93], v[138:141], v[188:191], v[90:93]
	v_mfma_f32_16x16x32_bf16 v[78:81], v[130:133], v[204:207], v[78:81]
	v_mfma_f32_16x16x32_bf16 v[74:77], v[138:141], v[204:207], v[74:77]
	v_mfma_f32_16x16x32_bf16 v[126:129], v[134:137], v[166:169], v[126:129]
	v_mfma_f32_16x16x32_bf16 v[122:125], v[142:145], v[166:169], v[122:125]
	v_mfma_f32_16x16x32_bf16 v[110:113], v[134:137], v[174:177], v[110:113]
	v_mfma_f32_16x16x32_bf16 v[106:109], v[142:145], v[174:177], v[106:109]
	v_mfma_f32_16x16x32_bf16 v[94:97], v[134:137], v[192:195], v[94:97]
	v_mfma_f32_16x16x32_bf16 v[90:93], v[142:145], v[192:195], v[90:93]
	v_mfma_f32_16x16x32_bf16 v[78:81], v[134:137], v[216:219], v[78:81]
	v_mfma_f32_16x16x32_bf16 v[74:77], v[142:145], v[216:219], v[74:77]
	s_setprio 0
	s_setprio 1
	v_mfma_f32_16x16x32_bf16 v[118:121], v[146:149], v[162:165], v[118:121]
	v_mfma_f32_16x16x32_bf16 v[114:117], v[154:157], v[162:165], v[114:117]
	v_mfma_f32_16x16x32_bf16 v[102:105], v[146:149], v[170:173], v[102:105]
	v_mfma_f32_16x16x32_bf16 v[98:101], v[154:157], v[170:173], v[98:101]
	v_mfma_f32_16x16x32_bf16 v[86:89], v[146:149], v[188:191], v[86:89]
	v_mfma_f32_16x16x32_bf16 v[82:85], v[154:157], v[188:191], v[82:85]
	v_mfma_f32_16x16x32_bf16 v[70:73], v[146:149], v[204:207], v[70:73]
	v_mfma_f32_16x16x32_bf16 v[66:69], v[154:157], v[204:207], v[66:69]
	v_mfma_f32_16x16x32_bf16 v[118:121], v[150:153], v[166:169], v[118:121]
	v_mfma_f32_16x16x32_bf16 v[114:117], v[158:161], v[166:169], v[114:117]
	v_mfma_f32_16x16x32_bf16 v[102:105], v[150:153], v[174:177], v[102:105]
	v_mfma_f32_16x16x32_bf16 v[98:101], v[158:161], v[174:177], v[98:101]
	v_mfma_f32_16x16x32_bf16 v[86:89], v[150:153], v[192:195], v[86:89]
	v_mfma_f32_16x16x32_bf16 v[82:85], v[158:161], v[192:195], v[82:85]
	v_mfma_f32_16x16x32_bf16 v[70:73], v[150:153], v[216:219], v[70:73]
	v_mfma_f32_16x16x32_bf16 v[66:69], v[158:161], v[216:219], v[66:69]
	s_barrier
	s_setprio 0
	s_add_i32 s29, s29, s15
	s_mov_b32 m0, s29
	ds_read_b128 v[162:165], v214 offset:16384
	ds_read_b128 v[166:169], v214 offset:17408
	ds_read_b128 v[170:173], v214 offset:18432
	ds_read_b128 v[174:177], v214 offset:19456
	ds_read_b128 v[188:191], v214 offset:20480
	ds_read_b128 v[192:195], v214 offset:21504
	ds_read_b128 v[204:207], v214 offset:22528
	ds_read_b128 v[216:219], v214 offset:23552
	global_load_lds_dwordx4 v0, s[66:67]
	s_add_i32 m0, s29, 0x2000
	s_add_u32 s46, s66, 0xb0000
	s_addc_u32 s47, s67, 0
	s_add_i32 s29, s48, s15
	global_load_lds_dwordx4 v182, s[66:67]
	s_mov_b32 m0, s29
	s_nop 0
	global_load_lds_dwordx4 v0, s[46:47]
	s_add_i32 m0, s29, 0x2000
	s_nop 0
	global_load_lds_dwordx4 v182, s[46:47]
	s_mov_b32 m0, s34
	s_nop 0
	global_load_lds_dwordx4 v178, s[72:73]
	s_mov_b32 m0, s12
	s_nop 0
	global_load_lds_dwordx4 v180, s[72:73]
	s_waitcnt vmcnt(8)
	s_waitcnt lgkmcnt(0)
	s_barrier
	s_setprio 1
	v_mfma_f32_16x16x32_bf16 v[62:65], v[130:133], v[162:165], v[62:65]
	v_mfma_f32_16x16x32_bf16 v[58:61], v[138:141], v[162:165], v[58:61]
	v_mfma_f32_16x16x32_bf16 v[46:49], v[130:133], v[170:173], v[46:49]
	v_mfma_f32_16x16x32_bf16 v[42:45], v[138:141], v[170:173], v[42:45]
	v_mfma_f32_16x16x32_bf16 v[30:33], v[130:133], v[188:191], v[30:33]
	v_mfma_f32_16x16x32_bf16 v[26:29], v[138:141], v[188:191], v[26:29]
	v_mfma_f32_16x16x32_bf16 v[14:17], v[130:133], v[204:207], v[14:17]
	v_mfma_f32_16x16x32_bf16 v[10:13], v[138:141], v[204:207], v[10:13]
	v_mfma_f32_16x16x32_bf16 v[62:65], v[134:137], v[166:169], v[62:65]
	v_mfma_f32_16x16x32_bf16 v[58:61], v[142:145], v[166:169], v[58:61]
	v_mfma_f32_16x16x32_bf16 v[46:49], v[134:137], v[174:177], v[46:49]
	v_mfma_f32_16x16x32_bf16 v[42:45], v[142:145], v[174:177], v[42:45]
	v_mfma_f32_16x16x32_bf16 v[30:33], v[134:137], v[192:195], v[30:33]
	v_mfma_f32_16x16x32_bf16 v[26:29], v[142:145], v[192:195], v[26:29]
	v_mfma_f32_16x16x32_bf16 v[14:17], v[134:137], v[216:219], v[14:17]
	v_mfma_f32_16x16x32_bf16 v[10:13], v[142:145], v[216:219], v[10:13]
	s_setprio 0
	s_setprio 1
	v_mfma_f32_16x16x32_bf16 v[54:57], v[146:149], v[162:165], v[54:57]
	v_mfma_f32_16x16x32_bf16 v[50:53], v[154:157], v[162:165], v[50:53]
	v_mfma_f32_16x16x32_bf16 v[38:41], v[146:149], v[170:173], v[38:41]
	v_mfma_f32_16x16x32_bf16 v[34:37], v[154:157], v[170:173], v[34:37]
	v_mfma_f32_16x16x32_bf16 v[22:25], v[146:149], v[188:191], v[22:25]
	v_mfma_f32_16x16x32_bf16 v[18:21], v[154:157], v[188:191], v[18:21]
	v_mfma_f32_16x16x32_bf16 v[6:9], v[146:149], v[204:207], v[6:9]
	v_mfma_f32_16x16x32_bf16 v[2:5], v[154:157], v[204:207], v[2:5]
	v_mfma_f32_16x16x32_bf16 v[54:57], v[150:153], v[166:169], v[54:57]
	v_mfma_f32_16x16x32_bf16 v[50:53], v[158:161], v[166:169], v[50:53]
	v_mfma_f32_16x16x32_bf16 v[38:41], v[150:153], v[174:177], v[38:41]
	v_mfma_f32_16x16x32_bf16 v[34:37], v[158:161], v[174:177], v[34:37]
	v_mfma_f32_16x16x32_bf16 v[22:25], v[150:153], v[192:195], v[22:25]
	v_mfma_f32_16x16x32_bf16 v[18:21], v[158:161], v[192:195], v[18:21]
	v_mfma_f32_16x16x32_bf16 v[6:9], v[150:153], v[216:219], v[6:9]
	v_mfma_f32_16x16x32_bf16 v[2:5], v[158:161], v[216:219], v[2:5]
	s_barrier
; #define PG8_STAGE(bufoff, gbase, voff) do { _Pragma("unroll") for (int _i = 0; _i < 2; ++_i) \
;         __builtin_amdgcn_global_load_lds((const gunsigned*)((const gchar*)(gbase) + (voff)[_i]), (LAS unsigned*)(lds + (bufoff) + ldsw + _i * 8192), 16, 0, 0); } while (0)
; #define PG8_LDA(dst, b, h) do { _Pragma("unroll") for (int m = 0; m < 4; ++m) _Pragma("unroll") for (int k = 0; k < 2; ++k) dst[m][k] = *(const LAS bf16x8*)(lds + PG8_SA(b, h) + aoff + m * 2048 + k * 1024); } while (0)
; #define PG8_LDB(dst, b, h) do { _Pragma("unroll") for (int n = 0; n < 2; ++n) _Pragma("unroll") for (int k = 0; k < 2; ++k) dst[n][k] = *(const LAS bf16x8*)(lds + PG8_SB(b, h) + boff + n * 2048 + k * 1024); } while (0)
; #define PG8_MMA(ai, bj, At, Bt) do { __builtin_amdgcn_s_setprio(1); _Pragma("unroll") for (int m = 0; m < 4; ++m) _Pragma("unroll") for (int n = 0; n < 2; ++n) _Pragma("unroll") for (int k = 0; k < 2; ++k) \
;         acc[ai][bj][m][n] = __builtin_amdgcn_mfma_f32_16x16x32_bf16(Bt[n][k], At[m][k], acc[ai][bj][m][n], 0, 0, 0); __builtin_amdgcn_s_setprio(0); } while (0)
; #define PG8_WAIT_V(n) asm volatile("s_waitcnt vmcnt(" #n ")" ::: "memory")
; #define PG8_WAIT_L(n) asm volatile("s_waitcnt lgkmcnt(" #n ")" ::: "memory")
; #define PG8_BAR __builtin_amdgcn_s_barrier()
; #define PG8_SCHED __builtin_amdgcn_sched_barrier(0)
; template <class Epi, class Sched>
; __device__ __forceinline__ void gemm_phase(LAS unsigned char* lds, const int tid, const Gemm g, const Sched& S, const Epi& E) {
;     ...
;             PG8_LDB(B0, 1, 0); PG8_LDB(B1, 1, 1); PG8_SCHED; PG8_LDA(At, 1, 0); PG8_STAGE(PG8_SA(0, 1), a2 + hstep, voffA);
;             PG8_WAIT_V(8); PG8_WAIT_L(0); PG8_BAR; PG8_MMA(0, 0, At, B0); PG8_MMA(0, 1, At, B1); PG8_BAR; PG8_SCHED;
;             PG8_LDA(At, 1, 1); PG8_STAGE(PG8_SB(1, 0), b3, voffB); PG8_STAGE(PG8_SB(1, 1), b3 + hstep, voffB); PG8_STAGE(PG8_SA(1, 0), a3, voffA);
;             PG8_WAIT_V(8); PG8_WAIT_L(0); PG8_BAR; PG8_MMA(1, 0, At, B0); PG8_MMA(1, 1, At, B1); PG8_BAR; PG8_SCHED;
;         }
	s_setprio 0
	s_add_i32 s29, 0, 0x18000
	s_add_i32 s48, 0, 0x1c000
	v_add_u32_e32 v142, s29, v210
	v_add_u32_e32 v158, s48, v210
	ds_read_b128 v[130:133], v142
	ds_read_b128 v[134:137], v142 offset:1024
	ds_read_b128 v[138:141], v142 offset:2048
	ds_read_b128 v[142:145], v142 offset:3072
	ds_read_b128 v[146:149], v158
	ds_read_b128 v[150:153], v158 offset:1024
	ds_read_b128 v[154:157], v158 offset:2048
	ds_read_b128 v[158:161], v158 offset:3072
	s_add_u32 s46, s72, 0xb0000
	s_addc_u32 s47, s73, 0
	s_mov_b32 m0, s35
	ds_read_b128 v[162:165], v214 offset:32768
	ds_read_b128 v[166:169], v214 offset:33792
	ds_read_b128 v[170:173], v214 offset:34816
	ds_read_b128 v[174:177], v214 offset:35840
	ds_read_b128 v[188:191], v214 offset:36864
	ds_read_b128 v[192:195], v214 offset:37888
	ds_read_b128 v[204:207], v214 offset:38912
	ds_read_b128 v[216:219], v214 offset:39936
	global_load_lds_dwordx4 v178, s[46:47]
	s_mov_b32 m0, s36
	s_nop 0
	global_load_lds_dwordx4 v180, s[46:47]
	s_waitcnt vmcnt(8)
	s_waitcnt lgkmcnt(0)
	s_barrier
	s_setprio 1
	v_mfma_f32_16x16x32_bf16 v[126:129], v[130:133], v[162:165], v[126:129]
	v_mfma_f32_16x16x32_bf16 v[122:125], v[138:141], v[162:165], v[122:125]
	v_mfma_f32_16x16x32_bf16 v[110:113], v[130:133], v[170:173], v[110:113]
	v_mfma_f32_16x16x32_bf16 v[106:109], v[138:141], v[170:173], v[106:109]
	v_mfma_f32_16x16x32_bf16 v[94:97], v[130:133], v[188:191], v[94:97]
	v_mfma_f32_16x16x32_bf16 v[90:93], v[138:141], v[188:191], v[90:93]
	v_mfma_f32_16x16x32_bf16 v[78:81], v[130:133], v[204:207], v[78:81]
	v_mfma_f32_16x16x32_bf16 v[74:77], v[138:141], v[204:207], v[74:77]
	v_mfma_f32_16x16x32_bf16 v[126:129], v[134:137], v[166:169], v[126:129]
	v_mfma_f32_16x16x32_bf16 v[122:125], v[142:145], v[166:169], v[122:125]
	v_mfma_f32_16x16x32_bf16 v[110:113], v[134:137], v[174:177], v[110:113]
	v_mfma_f32_16x16x32_bf16 v[106:109], v[142:145], v[174:177], v[106:109]
	v_mfma_f32_16x16x32_bf16 v[94:97], v[134:137], v[192:195], v[94:97]
	v_mfma_f32_16x16x32_bf16 v[90:93], v[142:145], v[192:195], v[90:93]
	v_mfma_f32_16x16x32_bf16 v[78:81], v[134:137], v[216:219], v[78:81]
	v_mfma_f32_16x16x32_bf16 v[74:77], v[142:145], v[216:219], v[74:77]
	s_setprio 0
	s_setprio 1
	v_mfma_f32_16x16x32_bf16 v[118:121], v[146:149], v[162:165], v[118:121]
	v_mfma_f32_16x16x32_bf16 v[114:117], v[154:157], v[162:165], v[114:117]
	v_mfma_f32_16x16x32_bf16 v[102:105], v[146:149], v[170:173], v[102:105]
	v_mfma_f32_16x16x32_bf16 v[98:101], v[154:157], v[170:173], v[98:101]
	v_mfma_f32_16x16x32_bf16 v[86:89], v[146:149], v[188:191], v[86:89]
	v_mfma_f32_16x16x32_bf16 v[82:85], v[154:157], v[188:191], v[82:85]
	v_mfma_f32_16x16x32_bf16 v[70:73], v[146:149], v[204:207], v[70:73]
	v_mfma_f32_16x16x32_bf16 v[66:69], v[154:157], v[204:207], v[66:69]
	v_mfma_f32_16x16x32_bf16 v[118:121], v[150:153], v[166:169], v[118:121]
	v_mfma_f32_16x16x32_bf16 v[114:117], v[158:161], v[166:169], v[114:117]
	v_mfma_f32_16x16x32_bf16 v[102:105], v[150:153], v[174:177], v[102:105]
	v_mfma_f32_16x16x32_bf16 v[98:101], v[158:161], v[174:177], v[98:101]
	v_mfma_f32_16x16x32_bf16 v[86:89], v[150:153], v[192:195], v[86:89]
	v_mfma_f32_16x16x32_bf16 v[82:85], v[158:161], v[192:195], v[82:85]
	v_mfma_f32_16x16x32_bf16 v[70:73], v[150:153], v[216:219], v[70:73]
	v_mfma_f32_16x16x32_bf16 v[66:69], v[158:161], v[216:219], v[66:69]
	s_barrier
	s_setprio 0
	s_add_i32 s29, s29, s15
	s_mov_b32 m0, s29
	ds_read_b128 v[162:165], v214 offset:49152
	ds_read_b128 v[166:169], v214 offset:50176
	ds_read_b128 v[170:173], v214 offset:51200
	ds_read_b128 v[174:177], v214 offset:52224
	ds_read_b128 v[188:191], v214 offset:53248
	ds_read_b128 v[192:195], v214 offset:54272
	ds_read_b128 v[204:207], v214 offset:55296
	ds_read_b128 v[216:219], v214 offset:56320
	global_load_lds_dwordx4 v221, s[66:67]
	s_add_i32 m0, s29, 0x2000
	s_add_u32 s46, s66, 0xb0080
	s_addc_u32 s47, s67, 0
	s_add_i32 s29, s48, s15
	global_load_lds_dwordx4 v223, s[66:67]
	s_mov_b32 m0, s29
	s_nop 0
	global_load_lds_dwordx4 v0, s[46:47]
	s_add_i32 m0, s29, 0x2000
	s_nop 0
	global_load_lds_dwordx4 v182, s[46:47]
	s_mov_b32 m0, s37
	s_nop 0
	global_load_lds_dwordx4 v225, s[72:73]
	s_mov_b32 m0, s38
	s_nop 0
	global_load_lds_dwordx4 v227, s[72:73]
	s_waitcnt vmcnt(8)
	s_waitcnt lgkmcnt(0)
	s_barrier
	s_setprio 1
	v_mfma_f32_16x16x32_bf16 v[62:65], v[130:133], v[162:165], v[62:65]
	v_mfma_f32_16x16x32_bf16 v[58:61], v[138:141], v[162:165], v[58:61]
	v_mfma_f32_16x16x32_bf16 v[46:49], v[130:133], v[170:173], v[46:49]
	v_mfma_f32_16x16x32_bf16 v[42:45], v[138:141], v[170:173], v[42:45]
	v_mfma_f32_16x16x32_bf16 v[30:33], v[130:133], v[188:191], v[30:33]
	v_mfma_f32_16x16x32_bf16 v[26:29], v[138:141], v[188:191], v[26:29]
	v_mfma_f32_16x16x32_bf16 v[14:17], v[130:133], v[204:207], v[14:17]
	v_mfma_f32_16x16x32_bf16 v[10:13], v[138:141], v[204:207], v[10:13]
	v_mfma_f32_16x16x32_bf16 v[62:65], v[134:137], v[166:169], v[62:65]
	v_mfma_f32_16x16x32_bf16 v[58:61], v[142:145], v[166:169], v[58:61]
	v_mfma_f32_16x16x32_bf16 v[46:49], v[134:137], v[174:177], v[46:49]
	v_mfma_f32_16x16x32_bf16 v[42:45], v[142:145], v[174:177], v[42:45]
	v_mfma_f32_16x16x32_bf16 v[30:33], v[134:137], v[192:195], v[30:33]
	v_mfma_f32_16x16x32_bf16 v[26:29], v[142:145], v[192:195], v[26:29]
	v_mfma_f32_16x16x32_bf16 v[14:17], v[134:137], v[216:219], v[14:17]
	v_mfma_f32_16x16x32_bf16 v[10:13], v[142:145], v[216:219], v[10:13]
	s_setprio 0
	s_setprio 1
	v_mfma_f32_16x16x32_bf16 v[54:57], v[146:149], v[162:165], v[54:57]
	v_mfma_f32_16x16x32_bf16 v[50:53], v[154:157], v[162:165], v[50:53]
	v_mfma_f32_16x16x32_bf16 v[38:41], v[146:149], v[170:173], v[38:41]
	v_mfma_f32_16x16x32_bf16 v[34:37], v[154:157], v[170:173], v[34:37]
	v_mfma_f32_16x16x32_bf16 v[22:25], v[146:149], v[188:191], v[22:25]
	v_mfma_f32_16x16x32_bf16 v[18:21], v[154:157], v[188:191], v[18:21]
	v_mfma_f32_16x16x32_bf16 v[6:9], v[146:149], v[204:207], v[6:9]
	v_mfma_f32_16x16x32_bf16 v[2:5], v[154:157], v[204:207], v[2:5]
	v_mfma_f32_16x16x32_bf16 v[54:57], v[150:153], v[166:169], v[54:57]
	v_mfma_f32_16x16x32_bf16 v[50:53], v[158:161], v[166:169], v[50:53]
	v_mfma_f32_16x16x32_bf16 v[38:41], v[150:153], v[174:177], v[38:41]
	v_mfma_f32_16x16x32_bf16 v[34:37], v[158:161], v[174:177], v[34:37]
	v_mfma_f32_16x16x32_bf16 v[22:25], v[150:153], v[192:195], v[22:25]
	v_mfma_f32_16x16x32_bf16 v[18:21], v[158:161], v[192:195], v[18:21]
	v_mfma_f32_16x16x32_bf16 v[6:9], v[150:153], v[216:219], v[6:9]
	v_mfma_f32_16x16x32_bf16 v[2:5], v[158:161], v[216:219], v[2:5]
	s_barrier
	s_setprio 0
	s_add_i32 s45, s45, 2
	s_add_u32 s31, s31, 0x100
	s_addc_u32 s44, s44, 0
	s_cmp_gt_u32 s45, 41
	s_mov_b64 s[62:63], s[20:21]
	s_cbranch_scc0 .LBB0_598
	s_and_b64 vcc, exec, s[58:59]
	s_cbranch_vccz .LBB0_601
	s_barrier

; #define PG8_STAGE(bufoff, gbase, voff) do { _Pragma("unroll") for (int _i = 0; _i < 2; ++_i) \
;         __builtin_amdgcn_global_load_lds((const gunsigned*)((const gchar*)(gbase) + (voff)[_i]), (LAS unsigned*)(lds + (bufoff) + ldsw + _i * 8192), 16, 0, 0); } while (0)
; #define PG8_LDA(dst, b, h) do { _Pragma("unroll") for (int m = 0; m < 4; ++m) _Pragma("unroll") for (int k = 0; k < 2; ++k) dst[m][k] = *(const LAS bf16x8*)(lds + PG8_SA(b, h) + aoff + m * 2048 + k * 1024); } while (0)
; #define PG8_LDB(dst, b, h) do { _Pragma("unroll") for (int n = 0; n < 2; ++n) _Pragma("unroll") for (int k = 0; k < 2; ++k) dst[n][k] = *(const LAS bf16x8*)(lds + PG8_SB(b, h) + boff + n * 2048 + k * 1024); } while (0)
; #define PG8_MMA(ai, bj, At, Bt) do { __builtin_amdgcn_s_setprio(1); _Pragma("unroll") for (int m = 0; m < 4; ++m) _Pragma("unroll") for (int n = 0; n < 2; ++n) _Pragma("unroll") for (int k = 0; k < 2; ++k) \
;         acc[ai][bj][m][n] = __builtin_amdgcn_mfma_f32_16x16x32_bf16(Bt[n][k], At[m][k], acc[ai][bj][m][n], 0, 0, 0); __builtin_amdgcn_s_setprio(0); } while (0)
; #define PG8_WAIT_V(n) asm volatile("s_waitcnt vmcnt(" #n ")" ::: "memory")
; #define PG8_WAIT_L(n) asm volatile("s_waitcnt lgkmcnt(" #n ")" ::: "memory")
; #define PG8_BAR __builtin_amdgcn_s_barrier()
; #define PG8_SCHED __builtin_amdgcn_sched_barrier(0)
; template <class Epi, class Sched>
; __device__ __forceinline__ void gemm_phase(LAS unsigned char* lds, const int tid, const Gemm g, const Sched& S, const Epi& E) {
;     ...
;         for (int t = 0; t < nt; t += 2) {
;             const bool last = (t == nt - 2);
;             const gchar* a1 = cA + (size_t)(t + 1) * kstep;
;             const gchar* a2 = last ? nA : cA + (size_t)(t + 2) * kstep; const gchar* b2 = last ? nB : cB + (size_t)(t + 2) * kstep;
;             const gchar* a3 = a2 + kstep; const gchar* b3 = b2 + kstep;
;             PG8_LDB(B0, 0, 0); PG8_LDB(B1, 0, 1); PG8_SCHED; PG8_LDA(At, 0, 0); PG8_STAGE(PG8_SA(1, 1), a1 + hstep, voffA);
;             PG8_WAIT_V(8); PG8_WAIT_L(0); PG8_BAR; PG8_MMA(0, 0, At, B0); PG8_MMA(0, 1, At, B1); PG8_BAR; PG8_SCHED;
;             PG8_LDA(At, 0, 1); PG8_STAGE(PG8_SB(0, 0), b2, voffB); PG8_STAGE(PG8_SB(0, 1), b2 + hstep, voffB); PG8_STAGE(PG8_SA(0, 0), a2, voffA);
;             PG8_WAIT_V(8); PG8_WAIT_L(0); PG8_BAR; PG8_MMA(1, 0, At, B0); PG8_MMA(1, 1, At, B1); PG8_BAR; PG8_SCHED;
.LBB0_647:
	s_add_u32 s20, s58, 0xfffc0080
	s_addc_u32 s21, s59, -1
	s_add_i32 s42, 0, 0x10000
	s_cmp_eq_u32 s41, 12
	s_cselect_b32 s61, s9, s21
	s_cselect_b32 s60, s37, s20
	v_add_u32_e32 v140, s42, v143
	s_cselect_b32 s21, s7, s40
	s_cselect_b32 s20, s38, s39
	s_add_i32 s44, 0, 0x14000
	ds_read_b128 v[146:149], v140
	ds_read_b128 v[150:153], v140 offset:1024
	ds_read_b128 v[154:157], v140 offset:2048
	ds_read_b128 v[158:161], v140 offset:3072
	v_add_u32_e32 v140, s44, v143
	ds_read_b128 v[162:165], v140
	ds_read_b128 v[166:169], v140 offset:1024
	ds_read_b128 v[170:173], v140 offset:2048
	ds_read_b128 v[174:177], v140 offset:3072
	s_add_i32 m0, s23, 0xc000
	ds_read_b128 v[178:181], v145
	ds_read_b128 v[182:185], v145 offset:1024
	ds_read_b128 v[186:189], v145 offset:2048
	ds_read_b128 v[190:193], v145 offset:3072
	ds_read_b128 v[204:207], v145 offset:4096
	ds_read_b128 v[208:211], v145 offset:5120
	ds_read_b128 v[212:215], v145 offset:6144
	ds_read_b128 v[216:219], v145 offset:7168
	global_load_lds_dwordx4 v138, s[58:59]
	s_add_i32 m0, s23, 0xe000
	s_nop 0
	global_load_lds_dwordx4 v136, s[58:59]
	s_waitcnt vmcnt(8)
	s_waitcnt lgkmcnt(0)
	s_barrier
	s_setprio 1
	v_mfma_f32_16x16x32_bf16 v[126:129], v[146:149], v[178:181], v[126:129]
	v_mfma_f32_16x16x32_bf16 v[122:125], v[154:157], v[178:181], v[122:125]
	v_mfma_f32_16x16x32_bf16 v[110:113], v[146:149], v[186:189], v[110:113]
	v_mfma_f32_16x16x32_bf16 v[106:109], v[154:157], v[186:189], v[106:109]
	v_mfma_f32_16x16x32_bf16 v[94:97], v[146:149], v[204:207], v[94:97]
	v_mfma_f32_16x16x32_bf16 v[90:93], v[154:157], v[204:207], v[90:93]
	v_mfma_f32_16x16x32_bf16 v[78:81], v[146:149], v[212:215], v[78:81]
	v_mfma_f32_16x16x32_bf16 v[74:77], v[154:157], v[212:215], v[74:77]
	v_mfma_f32_16x16x32_bf16 v[126:129], v[150:153], v[182:185], v[126:129]
	v_mfma_f32_16x16x32_bf16 v[122:125], v[158:161], v[182:185], v[122:125]
	v_mfma_f32_16x16x32_bf16 v[110:113], v[150:153], v[190:193], v[110:113]
	v_mfma_f32_16x16x32_bf16 v[106:109], v[158:161], v[190:193], v[106:109]
	v_mfma_f32_16x16x32_bf16 v[94:97], v[150:153], v[208:211], v[94:97]
	v_mfma_f32_16x16x32_bf16 v[90:93], v[158:161], v[208:211], v[90:93]
	v_mfma_f32_16x16x32_bf16 v[78:81], v[150:153], v[216:219], v[78:81]
	v_mfma_f32_16x16x32_bf16 v[74:77], v[158:161], v[216:219], v[74:77]
	s_setprio 0
	s_setprio 1
	v_mfma_f32_16x16x32_bf16 v[118:121], v[162:165], v[178:181], v[118:121]
	v_mfma_f32_16x16x32_bf16 v[114:117], v[170:173], v[178:181], v[114:117]
	v_mfma_f32_16x16x32_bf16 v[102:105], v[162:165], v[186:189], v[102:105]
	v_mfma_f32_16x16x32_bf16 v[98:101], v[170:173], v[186:189], v[98:101]
	v_mfma_f32_16x16x32_bf16 v[86:89], v[162:165], v[204:207], v[86:89]
	v_mfma_f32_16x16x32_bf16 v[82:85], v[170:173], v[204:207], v[82:85]
	v_mfma_f32_16x16x32_bf16 v[70:73], v[162:165], v[212:215], v[70:73]
	v_mfma_f32_16x16x32_bf16 v[66:69], v[170:173], v[212:215], v[66:69]
	v_mfma_f32_16x16x32_bf16 v[118:121], v[166:169], v[182:185], v[118:121]
	v_mfma_f32_16x16x32_bf16 v[114:117], v[174:177], v[182:185], v[114:117]
	v_mfma_f32_16x16x32_bf16 v[102:105], v[166:169], v[190:193], v[102:105]
	v_mfma_f32_16x16x32_bf16 v[98:101], v[174:177], v[190:193], v[98:101]
	v_mfma_f32_16x16x32_bf16 v[86:89], v[166:169], v[208:211], v[86:89]
	v_mfma_f32_16x16x32_bf16 v[82:85], v[174:177], v[208:211], v[82:85]
	v_mfma_f32_16x16x32_bf16 v[70:73], v[166:169], v[216:219], v[70:73]
	v_mfma_f32_16x16x32_bf16 v[66:69], v[174:177], v[216:219], v[66:69]
	s_barrier
	s_setprio 0
	s_add_i32 s42, s42, s12
	s_mov_b32 m0, s42
	ds_read_b128 v[178:181], v145 offset:16384
	ds_read_b128 v[182:185], v145 offset:17408
	ds_read_b128 v[186:189], v145 offset:18432
	ds_read_b128 v[190:193], v145 offset:19456
	ds_read_b128 v[204:207], v145 offset:20480
	ds_read_b128 v[208:211], v145 offset:21504
	ds_read_b128 v[212:215], v145 offset:22528
	ds_read_b128 v[216:219], v145 offset:23552
	global_load_lds_dwordx4 v0, s[20:21]
	s_add_i32 m0, s42, 0x2000
	s_add_u32 s42, s20, 0x40000
	s_addc_u32 s43, s21, 0
	s_add_i32 s44, s44, s12
	global_load_lds_dwordx4 v130, s[20:21]
	s_mov_b32 m0, s44
	s_nop 0
	global_load_lds_dwordx4 v0, s[42:43]
	s_add_i32 m0, s44, 0x2000
	s_nop 0
	global_load_lds_dwordx4 v130, s[42:43]
	s_mov_b32 m0, s23
	s_nop 0
	global_load_lds_dwordx4 v134, s[60:61]
	s_mov_b32 m0, s24
	s_nop 0
	global_load_lds_dwordx4 v132, s[60:61]
	s_waitcnt vmcnt(8)
	s_waitcnt lgkmcnt(0)
	s_barrier
	s_setprio 1
	v_mfma_f32_16x16x32_bf16 v[62:65], v[146:149], v[178:181], v[62:65]
	v_mfma_f32_16x16x32_bf16 v[58:61], v[154:157], v[178:181], v[58:61]
	v_mfma_f32_16x16x32_bf16 v[46:49], v[146:149], v[186:189], v[46:49]
	v_mfma_f32_16x16x32_bf16 v[42:45], v[154:157], v[186:189], v[42:45]
	v_mfma_f32_16x16x32_bf16 v[30:33], v[146:149], v[204:207], v[30:33]
	v_mfma_f32_16x16x32_bf16 v[26:29], v[154:157], v[204:207], v[26:29]
	v_mfma_f32_16x16x32_bf16 v[14:17], v[146:149], v[212:215], v[14:17]
	v_mfma_f32_16x16x32_bf16 v[10:13], v[154:157], v[212:215], v[10:13]
	v_mfma_f32_16x16x32_bf16 v[62:65], v[150:153], v[182:185], v[62:65]
	v_mfma_f32_16x16x32_bf16 v[58:61], v[158:161], v[182:185], v[58:61]
	v_mfma_f32_16x16x32_bf16 v[46:49], v[150:153], v[190:193], v[46:49]
	v_mfma_f32_16x16x32_bf16 v[42:45], v[158:161], v[190:193], v[42:45]
	v_mfma_f32_16x16x32_bf16 v[30:33], v[150:153], v[208:211], v[30:33]
	v_mfma_f32_16x16x32_bf16 v[26:29], v[158:161], v[208:211], v[26:29]
	v_mfma_f32_16x16x32_bf16 v[14:17], v[150:153], v[216:219], v[14:17]
	v_mfma_f32_16x16x32_bf16 v[10:13], v[158:161], v[216:219], v[10:13]
	s_setprio 0
	s_setprio 1
	v_mfma_f32_16x16x32_bf16 v[54:57], v[162:165], v[178:181], v[54:57]
	v_mfma_f32_16x16x32_bf16 v[50:53], v[170:173], v[178:181], v[50:53]
	v_mfma_f32_16x16x32_bf16 v[38:41], v[162:165], v[186:189], v[38:41]
	v_mfma_f32_16x16x32_bf16 v[34:37], v[170:173], v[186:189], v[34:37]
	v_mfma_f32_16x16x32_bf16 v[22:25], v[162:165], v[204:207], v[22:25]
	v_mfma_f32_16x16x32_bf16 v[18:21], v[170:173], v[204:207], v[18:21]
	v_mfma_f32_16x16x32_bf16 v[6:9], v[162:165], v[212:215], v[6:9]
	v_mfma_f32_16x16x32_bf16 v[2:5], v[170:173], v[212:215], v[2:5]
	v_mfma_f32_16x16x32_bf16 v[54:57], v[166:169], v[182:185], v[54:57]
	v_mfma_f32_16x16x32_bf16 v[50:53], v[174:177], v[182:185], v[50:53]
	v_mfma_f32_16x16x32_bf16 v[38:41], v[166:169], v[190:193], v[38:41]
	v_mfma_f32_16x16x32_bf16 v[34:37], v[174:177], v[190:193], v[34:37]
	v_mfma_f32_16x16x32_bf16 v[22:25], v[166:169], v[208:211], v[22:25]
	v_mfma_f32_16x16x32_bf16 v[18:21], v[174:177], v[208:211], v[18:21]
	v_mfma_f32_16x16x32_bf16 v[6:9], v[166:169], v[216:219], v[6:9]
	v_mfma_f32_16x16x32_bf16 v[2:5], v[174:177], v[216:219], v[2:5]
	s_barrier
; #define PG8_STAGE(bufoff, gbase, voff) do { _Pragma("unroll") for (int _i = 0; _i < 2; ++_i) \
;         __builtin_amdgcn_global_load_lds((const gunsigned*)((const gchar*)(gbase) + (voff)[_i]), (LAS unsigned*)(lds + (bufoff) + ldsw + _i * 8192), 16, 0, 0); } while (0)
; #define PG8_LDA(dst, b, h) do { _Pragma("unroll") for (int m = 0; m < 4; ++m) _Pragma("unroll") for (int k = 0; k < 2; ++k) dst[m][k] = *(const LAS bf16x8*)(lds + PG8_SA(b, h) + aoff + m * 2048 + k * 1024); } while (0)
; #define PG8_LDB(dst, b, h) do { _Pragma("unroll") for (int n = 0; n < 2; ++n) _Pragma("unroll") for (int k = 0; k < 2; ++k) dst[n][k] = *(const LAS bf16x8*)(lds + PG8_SB(b, h) + boff + n * 2048 + k * 1024); } while (0)
; #define PG8_MMA(ai, bj, At, Bt) do { __builtin_amdgcn_s_setprio(1); _Pragma("unroll") for (int m = 0; m < 4; ++m) _Pragma("unroll") for (int n = 0; n < 2; ++n) _Pragma("unroll") for (int k = 0; k < 2; ++k) \
;         acc[ai][bj][m][n] = __builtin_amdgcn_mfma_f32_16x16x32_bf16(Bt[n][k], At[m][k], acc[ai][bj][m][n], 0, 0, 0); __builtin_amdgcn_s_setprio(0); } while (0)
; #define PG8_WAIT_V(n) asm volatile("s_waitcnt vmcnt(" #n ")" ::: "memory")
; #define PG8_WAIT_L(n) asm volatile("s_waitcnt lgkmcnt(" #n ")" ::: "memory")
; #define PG8_BAR __builtin_amdgcn_s_barrier()
; #define PG8_SCHED __builtin_amdgcn_sched_barrier(0)
; template <class Epi, class Sched>
; __device__ __forceinline__ void gemm_phase(LAS unsigned char* lds, const int tid, const Gemm g, const Sched& S, const Epi& E) {
;     ...
;             PG8_LDB(B0, 1, 0); PG8_LDB(B1, 1, 1); PG8_SCHED; PG8_LDA(At, 1, 0); PG8_STAGE(PG8_SA(0, 1), a2 + hstep, voffA);
;             PG8_WAIT_V(8); PG8_WAIT_L(0); PG8_BAR; PG8_MMA(0, 0, At, B0); PG8_MMA(0, 1, At, B1); PG8_BAR; PG8_SCHED;
;             PG8_LDA(At, 1, 1); PG8_STAGE(PG8_SB(1, 0), b3, voffB); PG8_STAGE(PG8_SB(1, 1), b3 + hstep, voffB); PG8_STAGE(PG8_SA(1, 0), a3, voffA);
;             PG8_WAIT_V(8); PG8_WAIT_L(0); PG8_BAR; PG8_MMA(1, 0, At, B0); PG8_MMA(1, 1, At, B1); PG8_BAR; PG8_SCHED;
;         }
	s_setprio 0
	s_add_i32 s44, 0, 0x18000
	s_add_i32 s45, 0, 0x1c000
	v_add_u32_e32 v158, s44, v143
	v_add_u32_e32 v174, s45, v143
	ds_read_b128 v[146:149], v158
	ds_read_b128 v[150:153], v158 offset:1024
	ds_read_b128 v[154:157], v158 offset:2048
	ds_read_b128 v[158:161], v158 offset:3072
	ds_read_b128 v[162:165], v174
	ds_read_b128 v[166:169], v174 offset:1024
	ds_read_b128 v[170:173], v174 offset:2048
	ds_read_b128 v[174:177], v174 offset:3072
	s_add_u32 s42, s60, 0x40000
	s_addc_u32 s43, s61, 0
	s_mov_b32 m0, s29
	ds_read_b128 v[178:181], v145 offset:32768
	ds_read_b128 v[182:185], v145 offset:33792
	ds_read_b128 v[186:189], v145 offset:34816
	ds_read_b128 v[190:193], v145 offset:35840
	ds_read_b128 v[204:207], v145 offset:36864
	ds_read_b128 v[208:211], v145 offset:37888
	ds_read_b128 v[212:215], v145 offset:38912
	ds_read_b128 v[216:219], v145 offset:39936
	global_load_lds_dwordx4 v134, s[42:43]
	s_mov_b32 m0, s30
	s_nop 0
	global_load_lds_dwordx4 v132, s[42:43]
	s_waitcnt vmcnt(8)
	s_waitcnt lgkmcnt(0)
	s_barrier
	s_setprio 1
	v_mfma_f32_16x16x32_bf16 v[126:129], v[146:149], v[178:181], v[126:129]
	v_mfma_f32_16x16x32_bf16 v[122:125], v[154:157], v[178:181], v[122:125]
	v_mfma_f32_16x16x32_bf16 v[110:113], v[146:149], v[186:189], v[110:113]
	v_mfma_f32_16x16x32_bf16 v[106:109], v[154:157], v[186:189], v[106:109]
	v_mfma_f32_16x16x32_bf16 v[94:97], v[146:149], v[204:207], v[94:97]
	v_mfma_f32_16x16x32_bf16 v[90:93], v[154:157], v[204:207], v[90:93]
	v_mfma_f32_16x16x32_bf16 v[78:81], v[146:149], v[212:215], v[78:81]
	v_mfma_f32_16x16x32_bf16 v[74:77], v[154:157], v[212:215], v[74:77]
	v_mfma_f32_16x16x32_bf16 v[126:129], v[150:153], v[182:185], v[126:129]
	v_mfma_f32_16x16x32_bf16 v[122:125], v[158:161], v[182:185], v[122:125]
	v_mfma_f32_16x16x32_bf16 v[110:113], v[150:153], v[190:193], v[110:113]
	v_mfma_f32_16x16x32_bf16 v[106:109], v[158:161], v[190:193], v[106:109]
	v_mfma_f32_16x16x32_bf16 v[94:97], v[150:153], v[208:211], v[94:97]
	v_mfma_f32_16x16x32_bf16 v[90:93], v[158:161], v[208:211], v[90:93]
	v_mfma_f32_16x16x32_bf16 v[78:81], v[150:153], v[216:219], v[78:81]
	v_mfma_f32_16x16x32_bf16 v[74:77], v[158:161], v[216:219], v[74:77]
	s_setprio 0
	s_setprio 1
	v_mfma_f32_16x16x32_bf16 v[118:121], v[162:165], v[178:181], v[118:121]
	v_mfma_f32_16x16x32_bf16 v[114:117], v[170:173], v[178:181], v[114:117]
	v_mfma_f32_16x16x32_bf16 v[102:105], v[162:165], v[186:189], v[102:105]
	v_mfma_f32_16x16x32_bf16 v[98:101], v[170:173], v[186:189], v[98:101]
	v_mfma_f32_16x16x32_bf16 v[86:89], v[162:165], v[204:207], v[86:89]
	v_mfma_f32_16x16x32_bf16 v[82:85], v[170:173], v[204:207], v[82:85]
	v_mfma_f32_16x16x32_bf16 v[70:73], v[162:165], v[212:215], v[70:73]
	v_mfma_f32_16x16x32_bf16 v[66:69], v[170:173], v[212:215], v[66:69]
	v_mfma_f32_16x16x32_bf16 v[118:121], v[166:169], v[182:185], v[118:121]
	v_mfma_f32_16x16x32_bf16 v[114:117], v[174:177], v[182:185], v[114:117]
	v_mfma_f32_16x16x32_bf16 v[102:105], v[166:169], v[190:193], v[102:105]
	v_mfma_f32_16x16x32_bf16 v[98:101], v[174:177], v[190:193], v[98:101]
	v_mfma_f32_16x16x32_bf16 v[86:89], v[166:169], v[208:211], v[86:89]
	v_mfma_f32_16x16x32_bf16 v[82:85], v[174:177], v[208:211], v[82:85]
	v_mfma_f32_16x16x32_bf16 v[70:73], v[166:169], v[216:219], v[70:73]
	v_mfma_f32_16x16x32_bf16 v[66:69], v[174:177], v[216:219], v[66:69]
	s_barrier
	s_setprio 0
	s_add_i32 s42, s44, s12
	s_mov_b32 m0, s42
	ds_read_b128 v[178:181], v145 offset:49152
	ds_read_b128 v[182:185], v145 offset:50176
	ds_read_b128 v[186:189], v145 offset:51200
	ds_read_b128 v[190:193], v145 offset:52224
	ds_read_b128 v[204:207], v145 offset:53248
	ds_read_b128 v[208:211], v145 offset:54272
	ds_read_b128 v[212:215], v145 offset:55296
	ds_read_b128 v[216:219], v145 offset:56320
	global_load_lds_dwordx4 v141, s[20:21]
	s_add_i32 m0, s42, 0x2000
	s_add_i32 s42, s45, s12
	global_load_lds_dwordx4 v195, s[20:21]
	s_add_u32 s20, s20, 0x40080
	s_addc_u32 s21, s21, 0
	s_mov_b32 m0, s42
	s_nop 0
	global_load_lds_dwordx4 v0, s[20:21]
	s_add_i32 m0, s42, 0x2000
	s_nop 0
	global_load_lds_dwordx4 v130, s[20:21]
	s_mov_b32 m0, s31
	s_nop 0
	global_load_lds_dwordx4 v221, s[60:61]
	s_mov_b32 m0, s34
	s_nop 0
	global_load_lds_dwordx4 v223, s[60:61]
	s_waitcnt vmcnt(8)
	s_waitcnt lgkmcnt(0)
	s_barrier
	s_setprio 1
	v_mfma_f32_16x16x32_bf16 v[62:65], v[146:149], v[178:181], v[62:65]
	v_mfma_f32_16x16x32_bf16 v[58:61], v[154:157], v[178:181], v[58:61]
	v_mfma_f32_16x16x32_bf16 v[46:49], v[146:149], v[186:189], v[46:49]
	v_mfma_f32_16x16x32_bf16 v[42:45], v[154:157], v[186:189], v[42:45]
	v_mfma_f32_16x16x32_bf16 v[30:33], v[146:149], v[204:207], v[30:33]
	v_mfma_f32_16x16x32_bf16 v[26:29], v[154:157], v[204:207], v[26:29]
	v_mfma_f32_16x16x32_bf16 v[14:17], v[146:149], v[212:215], v[14:17]
	v_mfma_f32_16x16x32_bf16 v[10:13], v[154:157], v[212:215], v[10:13]
	v_mfma_f32_16x16x32_bf16 v[62:65], v[150:153], v[182:185], v[62:65]
	v_mfma_f32_16x16x32_bf16 v[58:61], v[158:161], v[182:185], v[58:61]
	v_mfma_f32_16x16x32_bf16 v[46:49], v[150:153], v[190:193], v[46:49]
	v_mfma_f32_16x16x32_bf16 v[42:45], v[158:161], v[190:193], v[42:45]
	v_mfma_f32_16x16x32_bf16 v[30:33], v[150:153], v[208:211], v[30:33]
	v_mfma_f32_16x16x32_bf16 v[26:29], v[158:161], v[208:211], v[26:29]
	v_mfma_f32_16x16x32_bf16 v[14:17], v[150:153], v[216:219], v[14:17]
	v_mfma_f32_16x16x32_bf16 v[10:13], v[158:161], v[216:219], v[10:13]
	s_setprio 0
	s_setprio 1
	v_mfma_f32_16x16x32_bf16 v[54:57], v[162:165], v[178:181], v[54:57]
	v_mfma_f32_16x16x32_bf16 v[50:53], v[170:173], v[178:181], v[50:53]
	v_mfma_f32_16x16x32_bf16 v[38:41], v[162:165], v[186:189], v[38:41]
	v_mfma_f32_16x16x32_bf16 v[34:37], v[170:173], v[186:189], v[34:37]
	v_mfma_f32_16x16x32_bf16 v[22:25], v[162:165], v[204:207], v[22:25]
	v_mfma_f32_16x16x32_bf16 v[18:21], v[170:173], v[204:207], v[18:21]
	v_mfma_f32_16x16x32_bf16 v[6:9], v[162:165], v[212:215], v[6:9]
	v_mfma_f32_16x16x32_bf16 v[2:5], v[170:173], v[212:215], v[2:5]
	v_mfma_f32_16x16x32_bf16 v[54:57], v[166:169], v[182:185], v[54:57]
	v_mfma_f32_16x16x32_bf16 v[50:53], v[174:177], v[182:185], v[50:53]
	v_mfma_f32_16x16x32_bf16 v[38:41], v[166:169], v[190:193], v[38:41]
	v_mfma_f32_16x16x32_bf16 v[34:37], v[174:177], v[190:193], v[34:37]
	v_mfma_f32_16x16x32_bf16 v[22:25], v[166:169], v[208:211], v[22:25]
	v_mfma_f32_16x16x32_bf16 v[18:21], v[174:177], v[208:211], v[18:21]
	v_mfma_f32_16x16x32_bf16 v[6:9], v[166:169], v[216:219], v[6:9]
	v_mfma_f32_16x16x32_bf16 v[2:5], v[174:177], v[216:219], v[2:5]
	s_barrier
	s_setprio 0
	s_add_i32 s41, s41, 2
	s_add_u32 s39, s39, 0x100
	s_addc_u32 s40, s40, 0
	s_add_u32 s58, s58, 0x100
	s_addc_u32 s59, s59, 0
	s_cmp_gt_u32 s41, 13
	s_cbranch_scc0 .LBB0_647
	s_and_b64 vcc, exec, s[4:5]
	s_cbranch_vccz .LBB0_650
	s_barrier
